# GEMM K-loops without the per-MFMA-block s_setprio toggles
# baseline (speedup 1.0000x reference)
; #define PG8_STAGE(bufoff, gbase, voff) do { _Pragma("unroll") for (int _i = 0; _i < 2; ++_i) \
;         __builtin_amdgcn_global_load_lds((const unsigned*)((const char*)(gbase) + (voff)[_i]), (PG8_LAS unsigned*)(lds + (bufoff) + ldsw + _i * 8192), 16, 0, 0); } while (0)
; #define PG8_LDA(dst, b, h) do { _Pragma("unroll") for (int m = 0; m < 4; ++m) _Pragma("unroll") for (int k = 0; k < 2; ++k) dst[m][k] = *(const PG8_LAS bf16x8*)(lds + PG8_SA(b, h) + aoff + m * 2048 + k * 1024); } while (0)
; #define PG8_LDB(dst, b, h) do { _Pragma("unroll") for (int n = 0; n < 2; ++n) _Pragma("unroll") for (int k = 0; k < 2; ++k) dst[n][k] = *(const PG8_LAS bf16x8*)(lds + PG8_SB(b, h) + boff + n * 2048 + k * 1024); } while (0)
; #define PG8_MMA(ai, bj, At, Bt) do { __builtin_amdgcn_s_setprio(1); _Pragma("unroll") for (int m = 0; m < 4; ++m) _Pragma("unroll") for (int n = 0; n < 2; ++n) _Pragma("unroll") for (int k = 0; k < 2; ++k) \
;         acc[ai][bj][m][n] = __builtin_amdgcn_mfma_f32_16x16x32_bf16(Bt[n][k], At[m][k], acc[ai][bj][m][n], 0, 0, 0); __builtin_amdgcn_s_setprio(0); } while (0)
; #define PG8_WAIT_V(n) asm volatile("s_waitcnt vmcnt(" #n ")" ::: "memory")
; #define PG8_WAIT_L(n) asm volatile("s_waitcnt lgkmcnt(" #n ")" ::: "memory")
; #define PG8_BAR __builtin_amdgcn_s_barrier()
; #define PG8_SCHED __builtin_amdgcn_sched_barrier(0)
; template <class Epi, class Sched, bool ALIGN_EPI = false, bool SP2 = false>
; __device__ __forceinline__ void gemm_phase(PG8_LAS unsigned char* lds, const Gemm g, const Sched& S, const Epi& E) {
;     ...
;             PG8_LDB(B0, 0, 0); PG8_LDB(B1, 0, 1); PG8_SCHED; PG8_LDA(At, 0, 0); PG8_STAGE(PG8_SA(1, 1), a1 + hstep, voffA);
;             PG8_WAIT_V(8); PG8_WAIT_L(0); PG8_BAR; PG8_MMA(0, 0, At, B0); PG8_MMA(0, 1, At, B1); PG8_BAR; PG8_SCHED;
;             PG8_LDA(At, 0, 1); PG8_STAGE(PG8_SB(0, 0), b2, voffB); PG8_STAGE(PG8_SB(0, 1), b2 + hstep, voffB); PG8_STAGE(PG8_SA(0, 0), a2, voffA);
;             PG8_WAIT_V(8); PG8_WAIT_L(0); PG8_BAR; PG8_MMA(1, 0, At, B0); PG8_MMA(1, 1, At, B1); PG8_BAR; PG8_SCHED;
.LBB0_198:
	ds_read_b128 v[144:147], v153
	ds_read_b128 v[156:159], v153 offset:1024
	ds_read_b128 v[160:163], v153 offset:2048
	ds_read_b128 v[164:167], v153 offset:3072
	ds_read_b128 v[168:171], v154
	ds_read_b128 v[172:175], v154 offset:1024
	ds_read_b128 v[176:179], v154 offset:2048
	ds_read_b128 v[180:183], v154 offset:3072
	s_add_u32 s34, s30, 0xfffc0080
	s_addc_u32 s35, s31, -1
	s_cmp_eq_u32 s61, 12
	s_cselect_b32 s37, s23, s35
	s_cselect_b32 s36, s57, s34
	s_cselect_b32 s35, s13, s60
	s_cselect_b32 s34, s58, s59
	v_lshl_add_u64 v[218:219], s[30:31], 0, v[136:137]
	s_add_i32 m0, s29, 0xc000
	ds_read_b128 v[184:187], v155
	ds_read_b128 v[188:191], v155 offset:1024
	ds_read_b128 v[192:195], v155 offset:2048
	ds_read_b128 v[196:199], v155 offset:3072
	ds_read_b128 v[200:203], v155 offset:4096
	ds_read_b128 v[204:207], v155 offset:5120
	ds_read_b128 v[210:213], v155 offset:6144
	ds_read_b128 v[214:217], v155 offset:7168
	global_load_lds_dwordx4 v[218:219], off
	v_lshl_add_u64 v[218:219], s[30:31], 0, v[138:139]
	s_add_i32 m0, s29, 0xe000
	s_nop 0
	global_load_lds_dwordx4 v[218:219], off
	s_waitcnt vmcnt(8)
	s_waitcnt lgkmcnt(0)
	s_barrier
	s_waitcnt lgkmcnt(0)
	v_mfma_f32_16x16x32_bf16 v[124:127], v[144:147], v[184:187], v[124:127]
	v_mfma_f32_16x16x32_bf16 v[116:119], v[160:163], v[184:187], v[116:119]
	v_mfma_f32_16x16x32_bf16 v[108:111], v[144:147], v[192:195], v[108:111]
	v_mfma_f32_16x16x32_bf16 v[100:103], v[160:163], v[192:195], v[100:103]
	v_mfma_f32_16x16x32_bf16 v[92:95], v[144:147], v[200:203], v[92:95]
	v_mfma_f32_16x16x32_bf16 v[84:87], v[160:163], v[200:203], v[84:87]
	v_mfma_f32_16x16x32_bf16 v[76:79], v[144:147], v[210:213], v[76:79]
	v_mfma_f32_16x16x32_bf16 v[68:71], v[160:163], v[210:213], v[68:71]
	v_mfma_f32_16x16x32_bf16 v[124:127], v[156:159], v[188:191], v[124:127]
	v_mfma_f32_16x16x32_bf16 v[116:119], v[164:167], v[188:191], v[116:119]
	v_mfma_f32_16x16x32_bf16 v[108:111], v[156:159], v[196:199], v[108:111]
	v_mfma_f32_16x16x32_bf16 v[100:103], v[164:167], v[196:199], v[100:103]
	v_mfma_f32_16x16x32_bf16 v[92:95], v[156:159], v[204:207], v[92:95]
	v_mfma_f32_16x16x32_bf16 v[84:87], v[164:167], v[204:207], v[84:87]
	v_mfma_f32_16x16x32_bf16 v[76:79], v[156:159], v[214:217], v[76:79]
	v_mfma_f32_16x16x32_bf16 v[68:71], v[164:167], v[214:217], v[68:71]
	v_mfma_f32_16x16x32_bf16 v[120:123], v[168:171], v[184:187], v[120:123]
	v_mfma_f32_16x16x32_bf16 v[112:115], v[176:179], v[184:187], v[112:115]
	v_mfma_f32_16x16x32_bf16 v[104:107], v[168:171], v[192:195], v[104:107]
	v_mfma_f32_16x16x32_bf16 v[96:99], v[176:179], v[192:195], v[96:99]
	v_mfma_f32_16x16x32_bf16 v[88:91], v[168:171], v[200:203], v[88:91]
	v_mfma_f32_16x16x32_bf16 v[80:83], v[176:179], v[200:203], v[80:83]
	v_mfma_f32_16x16x32_bf16 v[72:75], v[168:171], v[210:213], v[72:75]
	v_mfma_f32_16x16x32_bf16 v[64:67], v[176:179], v[210:213], v[64:67]
	v_mfma_f32_16x16x32_bf16 v[120:123], v[172:175], v[188:191], v[120:123]
	v_mfma_f32_16x16x32_bf16 v[112:115], v[180:183], v[188:191], v[112:115]
	v_mfma_f32_16x16x32_bf16 v[104:107], v[172:175], v[196:199], v[104:107]
	v_mfma_f32_16x16x32_bf16 v[96:99], v[180:183], v[196:199], v[96:99]
	v_mfma_f32_16x16x32_bf16 v[88:91], v[172:175], v[204:207], v[88:91]
	v_mfma_f32_16x16x32_bf16 v[80:83], v[180:183], v[204:207], v[80:83]
	v_mfma_f32_16x16x32_bf16 v[72:75], v[172:175], v[214:217], v[72:75]
	v_mfma_f32_16x16x32_bf16 v[64:67], v[180:183], v[214:217], v[64:67]
	s_barrier
	s_add_i32 s62, s51, s40
	v_lshl_add_u64 v[218:219], s[34:35], 0, v[130:131]
	s_mov_b32 m0, s62
	ds_read_b128 v[184:187], v155 offset:16384
	ds_read_b128 v[188:191], v155 offset:17408
	ds_read_b128 v[192:195], v155 offset:18432
	ds_read_b128 v[196:199], v155 offset:19456
	ds_read_b128 v[200:203], v155 offset:20480
	ds_read_b128 v[204:207], v155 offset:21504
	ds_read_b128 v[210:213], v155 offset:22528
	ds_read_b128 v[214:217], v155 offset:23552
	global_load_lds_dwordx4 v[218:219], off
	s_add_i32 m0, s62, 0x2000
	s_add_u32 s62, s34, 0x40000
	v_lshl_add_u64 v[220:221], s[34:35], 0, v[134:135]
	s_addc_u32 s63, s35, 0
	s_add_i32 s64, s52, s40
	global_load_lds_dwordx4 v[220:221], off
	v_lshl_add_u64 v[222:223], s[62:63], 0, v[130:131]
	s_mov_b32 m0, s64
	v_lshl_add_u64 v[224:225], s[36:37], 0, v[132:133]
	global_load_lds_dwordx4 v[222:223], off
	v_lshl_add_u64 v[222:223], s[62:63], 0, v[134:135]
	s_add_i32 m0, s64, 0x2000
	s_nop 0
	global_load_lds_dwordx4 v[222:223], off
	v_lshl_add_u64 v[222:223], s[36:37], 0, v[128:129]
	s_mov_b32 m0, s29
	s_nop 0
	global_load_lds_dwordx4 v[222:223], off
	s_mov_b32 m0, s43
	s_nop 0
	global_load_lds_dwordx4 v[224:225], off
	s_waitcnt vmcnt(8)
	s_waitcnt lgkmcnt(0)
	s_barrier
; #define PG8_STAGE(bufoff, gbase, voff) do { _Pragma("unroll") for (int _i = 0; _i < 2; ++_i) \
;         __builtin_amdgcn_global_load_lds((const unsigned*)((const char*)(gbase) + (voff)[_i]), (PG8_LAS unsigned*)(lds + (bufoff) + ldsw + _i * 8192), 16, 0, 0); } while (0)
; #define PG8_LDA(dst, b, h) do { _Pragma("unroll") for (int m = 0; m < 4; ++m) _Pragma("unroll") for (int k = 0; k < 2; ++k) dst[m][k] = *(const PG8_LAS bf16x8*)(lds + PG8_SA(b, h) + aoff + m * 2048 + k * 1024); } while (0)
; #define PG8_LDB(dst, b, h) do { _Pragma("unroll") for (int n = 0; n < 2; ++n) _Pragma("unroll") for (int k = 0; k < 2; ++k) dst[n][k] = *(const PG8_LAS bf16x8*)(lds + PG8_SB(b, h) + boff + n * 2048 + k * 1024); } while (0)
; #define PG8_MMA(ai, bj, At, Bt) do { __builtin_amdgcn_s_setprio(1); _Pragma("unroll") for (int m = 0; m < 4; ++m) _Pragma("unroll") for (int n = 0; n < 2; ++n) _Pragma("unroll") for (int k = 0; k < 2; ++k) \
;         acc[ai][bj][m][n] = __builtin_amdgcn_mfma_f32_16x16x32_bf16(Bt[n][k], At[m][k], acc[ai][bj][m][n], 0, 0, 0); __builtin_amdgcn_s_setprio(0); } while (0)
; #define PG8_WAIT_V(n) asm volatile("s_waitcnt vmcnt(" #n ")" ::: "memory")
; #define PG8_WAIT_L(n) asm volatile("s_waitcnt lgkmcnt(" #n ")" ::: "memory")
; #define PG8_BAR __builtin_amdgcn_s_barrier()
; #define PG8_SCHED __builtin_amdgcn_sched_barrier(0)
; template <class Epi, class Sched, bool ALIGN_EPI = false, bool SP2 = false>
; __device__ __forceinline__ void gemm_phase(PG8_LAS unsigned char* lds, const Gemm g, const Sched& S, const Epi& E) {
;     ...
;             PG8_WAIT_V(8); PG8_WAIT_L(0); PG8_BAR; PG8_MMA(1, 0, At, B0); PG8_MMA(1, 1, At, B1); PG8_BAR; PG8_SCHED;
;             PG8_LDB(B0, 1, 0); PG8_LDB(B1, 1, 1); PG8_SCHED; PG8_LDA(At, 1, 0); PG8_STAGE(PG8_SA(0, 1), a2 + hstep, voffA);
;             PG8_WAIT_V(8); PG8_WAIT_L(0); PG8_BAR; PG8_MMA(0, 0, At, B0); PG8_MMA(0, 1, At, B1); PG8_BAR; PG8_SCHED;
	s_waitcnt lgkmcnt(0)
	v_mfma_f32_16x16x32_bf16 v[60:63], v[144:147], v[184:187], v[60:63]
	v_mfma_f32_16x16x32_bf16 v[52:55], v[160:163], v[184:187], v[52:55]
	v_mfma_f32_16x16x32_bf16 v[44:47], v[144:147], v[192:195], v[44:47]
	v_mfma_f32_16x16x32_bf16 v[36:39], v[160:163], v[192:195], v[36:39]
	v_mfma_f32_16x16x32_bf16 v[28:31], v[144:147], v[200:203], v[28:31]
	v_mfma_f32_16x16x32_bf16 v[20:23], v[160:163], v[200:203], v[20:23]
	v_mfma_f32_16x16x32_bf16 v[12:15], v[144:147], v[210:213], v[12:15]
	v_mfma_f32_16x16x32_bf16 v[4:7], v[160:163], v[210:213], v[4:7]
	v_mfma_f32_16x16x32_bf16 v[60:63], v[156:159], v[188:191], v[60:63]
	v_mfma_f32_16x16x32_bf16 v[52:55], v[164:167], v[188:191], v[52:55]
	v_mfma_f32_16x16x32_bf16 v[44:47], v[156:159], v[196:199], v[44:47]
	v_mfma_f32_16x16x32_bf16 v[36:39], v[164:167], v[196:199], v[36:39]
	v_mfma_f32_16x16x32_bf16 v[28:31], v[156:159], v[204:207], v[28:31]
	v_mfma_f32_16x16x32_bf16 v[20:23], v[164:167], v[204:207], v[20:23]
	v_mfma_f32_16x16x32_bf16 v[12:15], v[156:159], v[214:217], v[12:15]
	v_mfma_f32_16x16x32_bf16 v[4:7], v[164:167], v[214:217], v[4:7]
	v_mfma_f32_16x16x32_bf16 v[56:59], v[168:171], v[184:187], v[56:59]
	v_mfma_f32_16x16x32_bf16 v[48:51], v[176:179], v[184:187], v[48:51]
	v_mfma_f32_16x16x32_bf16 v[40:43], v[168:171], v[192:195], v[40:43]
	v_mfma_f32_16x16x32_bf16 v[32:35], v[176:179], v[192:195], v[32:35]
	v_mfma_f32_16x16x32_bf16 v[24:27], v[168:171], v[200:203], v[24:27]
	v_mfma_f32_16x16x32_bf16 v[16:19], v[176:179], v[200:203], v[16:19]
	v_mfma_f32_16x16x32_bf16 v[8:11], v[168:171], v[210:213], v[8:11]
	v_mfma_f32_16x16x32_bf16 v[0:3], v[176:179], v[210:213], v[0:3]
	v_mfma_f32_16x16x32_bf16 v[56:59], v[172:175], v[188:191], v[56:59]
	v_mfma_f32_16x16x32_bf16 v[48:51], v[180:183], v[188:191], v[48:51]
	v_mfma_f32_16x16x32_bf16 v[40:43], v[172:175], v[196:199], v[40:43]
	v_mfma_f32_16x16x32_bf16 v[32:35], v[180:183], v[196:199], v[32:35]
	v_mfma_f32_16x16x32_bf16 v[24:27], v[172:175], v[204:207], v[24:27]
	v_mfma_f32_16x16x32_bf16 v[16:19], v[180:183], v[204:207], v[16:19]
	v_mfma_f32_16x16x32_bf16 v[8:11], v[172:175], v[214:217], v[8:11]
	v_mfma_f32_16x16x32_bf16 v[0:3], v[180:183], v[214:217], v[0:3]
	s_barrier
	s_add_i32 s62, 0, 0x18000
	s_add_i32 s63, 0, 0x1c000
	v_add_u32_e32 v164, s62, v151
	v_add_u32_e32 v180, s63, v151
	ds_read_b128 v[144:147], v164
	ds_read_b128 v[156:159], v164 offset:1024
	ds_read_b128 v[160:163], v164 offset:2048
	ds_read_b128 v[164:167], v164 offset:3072
	ds_read_b128 v[168:171], v180
	ds_read_b128 v[172:175], v180 offset:1024
	ds_read_b128 v[176:179], v180 offset:2048
	ds_read_b128 v[180:183], v180 offset:3072
	s_add_u32 s36, s36, 0x40000
	s_addc_u32 s37, s37, 0
	s_mov_b32 m0, s44
	v_lshl_add_u64 v[226:227], s[36:37], 0, v[128:129]
	ds_read_b128 v[184:187], v155 offset:32768
	ds_read_b128 v[188:191], v155 offset:33792
	ds_read_b128 v[192:195], v155 offset:34816
	ds_read_b128 v[196:199], v155 offset:35840
	ds_read_b128 v[200:203], v155 offset:36864
	ds_read_b128 v[204:207], v155 offset:37888
	ds_read_b128 v[210:213], v155 offset:38912
	ds_read_b128 v[214:217], v155 offset:39936
	global_load_lds_dwordx4 v[226:227], off
	v_lshl_add_u64 v[226:227], s[36:37], 0, v[132:133]
	s_mov_b32 m0, s45
	s_nop 0
	global_load_lds_dwordx4 v[226:227], off
	s_waitcnt vmcnt(8)
	s_waitcnt lgkmcnt(0)
	s_barrier
	s_waitcnt lgkmcnt(0)
	v_mfma_f32_16x16x32_bf16 v[124:127], v[144:147], v[184:187], v[124:127]
	v_mfma_f32_16x16x32_bf16 v[116:119], v[160:163], v[184:187], v[116:119]
	v_mfma_f32_16x16x32_bf16 v[108:111], v[144:147], v[192:195], v[108:111]
	v_mfma_f32_16x16x32_bf16 v[100:103], v[160:163], v[192:195], v[100:103]
	v_mfma_f32_16x16x32_bf16 v[92:95], v[144:147], v[200:203], v[92:95]
	v_mfma_f32_16x16x32_bf16 v[84:87], v[160:163], v[200:203], v[84:87]
	v_mfma_f32_16x16x32_bf16 v[76:79], v[144:147], v[210:213], v[76:79]
	v_mfma_f32_16x16x32_bf16 v[68:71], v[160:163], v[210:213], v[68:71]
	v_mfma_f32_16x16x32_bf16 v[124:127], v[156:159], v[188:191], v[124:127]
	v_mfma_f32_16x16x32_bf16 v[116:119], v[164:167], v[188:191], v[116:119]
	v_mfma_f32_16x16x32_bf16 v[108:111], v[156:159], v[196:199], v[108:111]
	v_mfma_f32_16x16x32_bf16 v[100:103], v[164:167], v[196:199], v[100:103]
	v_mfma_f32_16x16x32_bf16 v[92:95], v[156:159], v[204:207], v[92:95]
	v_mfma_f32_16x16x32_bf16 v[84:87], v[164:167], v[204:207], v[84:87]
	v_mfma_f32_16x16x32_bf16 v[76:79], v[156:159], v[214:217], v[76:79]
	v_mfma_f32_16x16x32_bf16 v[68:71], v[164:167], v[214:217], v[68:71]
	v_mfma_f32_16x16x32_bf16 v[120:123], v[168:171], v[184:187], v[120:123]
	v_mfma_f32_16x16x32_bf16 v[112:115], v[176:179], v[184:187], v[112:115]
	v_mfma_f32_16x16x32_bf16 v[104:107], v[168:171], v[192:195], v[104:107]
	v_mfma_f32_16x16x32_bf16 v[96:99], v[176:179], v[192:195], v[96:99]
	v_mfma_f32_16x16x32_bf16 v[88:91], v[168:171], v[200:203], v[88:91]
	v_mfma_f32_16x16x32_bf16 v[80:83], v[176:179], v[200:203], v[80:83]
	v_mfma_f32_16x16x32_bf16 v[72:75], v[168:171], v[210:213], v[72:75]
	v_mfma_f32_16x16x32_bf16 v[64:67], v[176:179], v[210:213], v[64:67]
	v_mfma_f32_16x16x32_bf16 v[120:123], v[172:175], v[188:191], v[120:123]
	v_mfma_f32_16x16x32_bf16 v[112:115], v[180:183], v[188:191], v[112:115]
	v_mfma_f32_16x16x32_bf16 v[104:107], v[172:175], v[196:199], v[104:107]
	v_mfma_f32_16x16x32_bf16 v[96:99], v[180:183], v[196:199], v[96:99]
	v_mfma_f32_16x16x32_bf16 v[88:91], v[172:175], v[204:207], v[88:91]
	v_mfma_f32_16x16x32_bf16 v[80:83], v[180:183], v[204:207], v[80:83]
	v_mfma_f32_16x16x32_bf16 v[72:75], v[172:175], v[214:217], v[72:75]
	v_mfma_f32_16x16x32_bf16 v[64:67], v[180:183], v[214:217], v[64:67]
	s_barrier
; #define PG8_STAGE(bufoff, gbase, voff) do { _Pragma("unroll") for (int _i = 0; _i < 2; ++_i) \
;         __builtin_amdgcn_global_load_lds((const unsigned*)((const char*)(gbase) + (voff)[_i]), (PG8_LAS unsigned*)(lds + (bufoff) + ldsw + _i * 8192), 16, 0, 0); } while (0)
; #define PG8_LDA(dst, b, h) do { _Pragma("unroll") for (int m = 0; m < 4; ++m) _Pragma("unroll") for (int k = 0; k < 2; ++k) dst[m][k] = *(const PG8_LAS bf16x8*)(lds + PG8_SA(b, h) + aoff + m * 2048 + k * 1024); } while (0)
; #define PG8_MMA(ai, bj, At, Bt) do { __builtin_amdgcn_s_setprio(1); _Pragma("unroll") for (int m = 0; m < 4; ++m) _Pragma("unroll") for (int n = 0; n < 2; ++n) _Pragma("unroll") for (int k = 0; k < 2; ++k) \
;         acc[ai][bj][m][n] = __builtin_amdgcn_mfma_f32_16x16x32_bf16(Bt[n][k], At[m][k], acc[ai][bj][m][n], 0, 0, 0); __builtin_amdgcn_s_setprio(0); } while (0)
; #define PG8_WAIT_V(n) asm volatile("s_waitcnt vmcnt(" #n ")" ::: "memory")
; #define PG8_WAIT_L(n) asm volatile("s_waitcnt lgkmcnt(" #n ")" ::: "memory")
; #define PG8_BAR __builtin_amdgcn_s_barrier()
; #define PG8_SCHED __builtin_amdgcn_sched_barrier(0)
; template <class Epi, class Sched, bool ALIGN_EPI = false, bool SP2 = false>
; __device__ __forceinline__ void gemm_phase(PG8_LAS unsigned char* lds, const Gemm g, const Sched& S, const Epi& E) {
;     ...
;         for (int t = 0; t < nt; t += 2) {
;             const bool last = (t == nt - 2);
;             const char* a1 = cA + (size_t)(t + 1) * kstep;
;             const char* a2 = last ? nA : cA + (size_t)(t + 2) * kstep; const char* b2 = last ? nB : cB + (size_t)(t + 2) * kstep;
;             const char* a3 = a2 + kstep; const char* b3 = b2 + kstep;
;             if (last && has_next) S.a_ready(nxt);
;     ...
;             PG8_LDA(At, 1, 1); PG8_STAGE(PG8_SB(1, 0), b3, voffB); PG8_STAGE(PG8_SB(1, 1), b3 + hstep, voffB); PG8_STAGE(PG8_SA(1, 0), a3, voffA);
;             PG8_WAIT_V(8); PG8_WAIT_L(0); PG8_BAR; PG8_MMA(1, 0, At, B0); PG8_MMA(1, 1, At, B1); PG8_BAR; PG8_SCHED;
	s_add_i32 s36, s62, s40
	v_lshl_add_u64 v[218:219], v[218:219], 0, s[8:9]
	s_mov_b32 m0, s36
	ds_read_b128 v[184:187], v155 offset:49152
	ds_read_b128 v[188:191], v155 offset:50176
	ds_read_b128 v[192:195], v155 offset:51200
	ds_read_b128 v[196:199], v155 offset:52224
	ds_read_b128 v[200:203], v155 offset:53248
	ds_read_b128 v[204:207], v155 offset:54272
	ds_read_b128 v[210:213], v155 offset:55296
	ds_read_b128 v[214:217], v155 offset:56320
	global_load_lds_dwordx4 v[218:219], off
	s_add_i32 m0, s36, 0x2000
	s_add_u32 s34, s34, 0x40080
	v_lshl_add_u64 v[218:219], v[220:221], 0, s[8:9]
	s_addc_u32 s35, s35, 0
	s_add_i32 s36, s63, s40
	global_load_lds_dwordx4 v[218:219], off
	v_lshl_add_u64 v[218:219], s[34:35], 0, v[130:131]
	s_mov_b32 m0, s36
	s_nop 0
	global_load_lds_dwordx4 v[218:219], off
	v_lshl_add_u64 v[218:219], s[34:35], 0, v[134:135]
	s_add_i32 m0, s36, 0x2000
	s_nop 0
	global_load_lds_dwordx4 v[218:219], off
	v_lshl_add_u64 v[218:219], v[222:223], 0, s[8:9]
	s_mov_b32 m0, s48
	s_nop 0
	global_load_lds_dwordx4 v[218:219], off
	v_lshl_add_u64 v[218:219], v[224:225], 0, s[8:9]
	s_mov_b32 m0, s49
	s_nop 0
	global_load_lds_dwordx4 v[218:219], off
	s_waitcnt vmcnt(8)
	s_waitcnt lgkmcnt(0)
	s_barrier
	s_waitcnt lgkmcnt(0)
	v_mfma_f32_16x16x32_bf16 v[60:63], v[144:147], v[184:187], v[60:63]
	v_mfma_f32_16x16x32_bf16 v[52:55], v[160:163], v[184:187], v[52:55]
	v_mfma_f32_16x16x32_bf16 v[44:47], v[144:147], v[192:195], v[44:47]
	v_mfma_f32_16x16x32_bf16 v[36:39], v[160:163], v[192:195], v[36:39]
	v_mfma_f32_16x16x32_bf16 v[28:31], v[144:147], v[200:203], v[28:31]
	v_mfma_f32_16x16x32_bf16 v[20:23], v[160:163], v[200:203], v[20:23]
	v_mfma_f32_16x16x32_bf16 v[12:15], v[144:147], v[210:213], v[12:15]
	v_mfma_f32_16x16x32_bf16 v[4:7], v[160:163], v[210:213], v[4:7]
	v_mfma_f32_16x16x32_bf16 v[60:63], v[156:159], v[188:191], v[60:63]
	v_mfma_f32_16x16x32_bf16 v[52:55], v[164:167], v[188:191], v[52:55]
	v_mfma_f32_16x16x32_bf16 v[44:47], v[156:159], v[196:199], v[44:47]
	v_mfma_f32_16x16x32_bf16 v[36:39], v[164:167], v[196:199], v[36:39]
	v_mfma_f32_16x16x32_bf16 v[28:31], v[156:159], v[204:207], v[28:31]
	v_mfma_f32_16x16x32_bf16 v[20:23], v[164:167], v[204:207], v[20:23]
	v_mfma_f32_16x16x32_bf16 v[12:15], v[156:159], v[214:217], v[12:15]
	v_mfma_f32_16x16x32_bf16 v[4:7], v[164:167], v[214:217], v[4:7]
	v_mfma_f32_16x16x32_bf16 v[56:59], v[168:171], v[184:187], v[56:59]
	v_mfma_f32_16x16x32_bf16 v[48:51], v[176:179], v[184:187], v[48:51]
	v_mfma_f32_16x16x32_bf16 v[40:43], v[168:171], v[192:195], v[40:43]
	v_mfma_f32_16x16x32_bf16 v[32:35], v[176:179], v[192:195], v[32:35]
	v_mfma_f32_16x16x32_bf16 v[24:27], v[168:171], v[200:203], v[24:27]
	v_mfma_f32_16x16x32_bf16 v[16:19], v[176:179], v[200:203], v[16:19]
	v_mfma_f32_16x16x32_bf16 v[8:11], v[168:171], v[210:213], v[8:11]
	v_mfma_f32_16x16x32_bf16 v[0:3], v[176:179], v[210:213], v[0:3]
	v_mfma_f32_16x16x32_bf16 v[56:59], v[172:175], v[188:191], v[56:59]
	v_mfma_f32_16x16x32_bf16 v[48:51], v[180:183], v[188:191], v[48:51]
	v_mfma_f32_16x16x32_bf16 v[40:43], v[172:175], v[196:199], v[40:43]
	v_mfma_f32_16x16x32_bf16 v[32:35], v[180:183], v[196:199], v[32:35]
	v_mfma_f32_16x16x32_bf16 v[24:27], v[172:175], v[204:207], v[24:27]
	v_mfma_f32_16x16x32_bf16 v[16:19], v[180:183], v[204:207], v[16:19]
	v_mfma_f32_16x16x32_bf16 v[8:11], v[172:175], v[214:217], v[8:11]
	v_mfma_f32_16x16x32_bf16 v[0:3], v[180:183], v[214:217], v[0:3]
	s_barrier
	s_add_i32 s61, s61, 2
	s_add_u32 s30, s30, 0x100
	s_addc_u32 s31, s31, 0
	s_add_u32 s59, s59, 0x100
	s_addc_u32 s60, s60, 0
	s_cmp_gt_u32 s61, 13
	s_cbranch_scc0 .LBB0_198
	s_and_b64 vcc, exec, s[10:11]
	s_cbranch_vccz .LBB0_201
	s_barrier

; #define PG8_STAGE(bufoff, gbase, voff) do { _Pragma("unroll") for (int _i = 0; _i < 2; ++_i) \
;         __builtin_amdgcn_global_load_lds((const unsigned*)((const char*)(gbase) + (voff)[_i]), (PG8_LAS unsigned*)(lds + (bufoff) + ldsw + _i * 8192), 16, 0, 0); } while (0)
; #define PG8_LDA(dst, b, h) do { _Pragma("unroll") for (int m = 0; m < 4; ++m) _Pragma("unroll") for (int k = 0; k < 2; ++k) dst[m][k] = *(const PG8_LAS bf16x8*)(lds + PG8_SA(b, h) + aoff + m * 2048 + k * 1024); } while (0)
; #define PG8_LDB(dst, b, h) do { _Pragma("unroll") for (int n = 0; n < 2; ++n) _Pragma("unroll") for (int k = 0; k < 2; ++k) dst[n][k] = *(const PG8_LAS bf16x8*)(lds + PG8_SB(b, h) + boff + n * 2048 + k * 1024); } while (0)
; #define PG8_MMA(ai, bj, At, Bt) do { __builtin_amdgcn_s_setprio(1); _Pragma("unroll") for (int m = 0; m < 4; ++m) _Pragma("unroll") for (int n = 0; n < 2; ++n) _Pragma("unroll") for (int k = 0; k < 2; ++k) \
;         acc[ai][bj][m][n] = __builtin_amdgcn_mfma_f32_16x16x32_bf16(Bt[n][k], At[m][k], acc[ai][bj][m][n], 0, 0, 0); __builtin_amdgcn_s_setprio(0); } while (0)
; #define PG8_WAIT_V(n) asm volatile("s_waitcnt vmcnt(" #n ")" ::: "memory")
; #define PG8_WAIT_L(n) asm volatile("s_waitcnt lgkmcnt(" #n ")" ::: "memory")
; #define PG8_BAR __builtin_amdgcn_s_barrier()
; #define PG8_SCHED __builtin_amdgcn_sched_barrier(0)
; template <class Epi, class Sched, bool ALIGN_EPI = false, bool SP2 = false>
; __device__ __forceinline__ void gemm_phase(PG8_LAS unsigned char* lds, const Gemm g, const Sched& S, const Epi& E) {
;     ...
;             PG8_LDB(B0, 0, 0); PG8_LDB(B1, 0, 1); PG8_SCHED; PG8_LDA(At, 0, 0); PG8_STAGE(PG8_SA(1, 1), a1 + hstep, voffA);
;             PG8_WAIT_V(8); PG8_WAIT_L(0); PG8_BAR; PG8_MMA(0, 0, At, B0); PG8_MMA(0, 1, At, B1); PG8_BAR; PG8_SCHED;
;             PG8_LDA(At, 0, 1); PG8_STAGE(PG8_SB(0, 0), b2, voffB); PG8_STAGE(PG8_SB(0, 1), b2 + hstep, voffB); PG8_STAGE(PG8_SA(0, 0), a2, voffA);
;             PG8_WAIT_V(8); PG8_WAIT_L(0); PG8_BAR; PG8_MMA(1, 0, At, B0); PG8_MMA(1, 1, At, B1); PG8_BAR; PG8_SCHED;
.LBB0_314:
	ds_read_b128 v[144:147], v152
	ds_read_b128 v[156:159], v152 offset:1024
	ds_read_b128 v[160:163], v152 offset:2048
	ds_read_b128 v[164:167], v152 offset:3072
	ds_read_b128 v[168:171], v153
	ds_read_b128 v[172:175], v153 offset:1024
	ds_read_b128 v[176:179], v153 offset:2048
	ds_read_b128 v[180:183], v153 offset:3072
	s_add_u32 s26, s24, 0xfff50080
	s_addc_u32 s27, s25, -1
	s_cmp_eq_u32 s57, 40
	s_cselect_b32 s29, s1, s27
	s_cselect_b32 s28, s0, s26
	s_cselect_b32 s27, s23, s56
	s_cselect_b32 s26, s22, s53
	v_lshl_add_u64 v[218:219], s[24:25], 0, v[136:137]
	s_add_i32 m0, s37, 0xc000
	ds_read_b128 v[184:187], v154
	ds_read_b128 v[188:191], v154 offset:1024
	ds_read_b128 v[192:195], v154 offset:2048
	ds_read_b128 v[196:199], v154 offset:3072
	ds_read_b128 v[200:203], v154 offset:4096
	ds_read_b128 v[204:207], v154 offset:5120
	ds_read_b128 v[210:213], v154 offset:6144
	ds_read_b128 v[214:217], v154 offset:7168
	global_load_lds_dwordx4 v[218:219], off
	v_lshl_add_u64 v[218:219], s[24:25], 0, v[138:139]
	s_add_i32 m0, s37, 0xe000
	s_nop 0
	global_load_lds_dwordx4 v[218:219], off
	s_waitcnt vmcnt(8)
	s_waitcnt lgkmcnt(0)
	s_barrier
	s_waitcnt lgkmcnt(0)
	v_mfma_f32_16x16x32_bf16 v[124:127], v[144:147], v[184:187], v[124:127]
	v_mfma_f32_16x16x32_bf16 v[120:123], v[160:163], v[184:187], v[120:123]
	v_mfma_f32_16x16x32_bf16 v[108:111], v[144:147], v[192:195], v[108:111]
	v_mfma_f32_16x16x32_bf16 v[104:107], v[160:163], v[192:195], v[104:107]
	v_mfma_f32_16x16x32_bf16 v[92:95], v[144:147], v[200:203], v[92:95]
	v_mfma_f32_16x16x32_bf16 v[88:91], v[160:163], v[200:203], v[88:91]
	v_mfma_f32_16x16x32_bf16 v[76:79], v[144:147], v[210:213], v[76:79]
	v_mfma_f32_16x16x32_bf16 v[72:75], v[160:163], v[210:213], v[72:75]
	v_mfma_f32_16x16x32_bf16 v[124:127], v[156:159], v[188:191], v[124:127]
	v_mfma_f32_16x16x32_bf16 v[120:123], v[164:167], v[188:191], v[120:123]
	v_mfma_f32_16x16x32_bf16 v[108:111], v[156:159], v[196:199], v[108:111]
	v_mfma_f32_16x16x32_bf16 v[104:107], v[164:167], v[196:199], v[104:107]
	v_mfma_f32_16x16x32_bf16 v[92:95], v[156:159], v[204:207], v[92:95]
	v_mfma_f32_16x16x32_bf16 v[88:91], v[164:167], v[204:207], v[88:91]
	v_mfma_f32_16x16x32_bf16 v[76:79], v[156:159], v[214:217], v[76:79]
	v_mfma_f32_16x16x32_bf16 v[72:75], v[164:167], v[214:217], v[72:75]
	v_mfma_f32_16x16x32_bf16 v[116:119], v[168:171], v[184:187], v[116:119]
	v_mfma_f32_16x16x32_bf16 v[112:115], v[176:179], v[184:187], v[112:115]
	v_mfma_f32_16x16x32_bf16 v[100:103], v[168:171], v[192:195], v[100:103]
	v_mfma_f32_16x16x32_bf16 v[96:99], v[176:179], v[192:195], v[96:99]
	v_mfma_f32_16x16x32_bf16 v[84:87], v[168:171], v[200:203], v[84:87]
	v_mfma_f32_16x16x32_bf16 v[80:83], v[176:179], v[200:203], v[80:83]
	v_mfma_f32_16x16x32_bf16 v[68:71], v[168:171], v[210:213], v[68:71]
	v_mfma_f32_16x16x32_bf16 v[64:67], v[176:179], v[210:213], v[64:67]
	v_mfma_f32_16x16x32_bf16 v[116:119], v[172:175], v[188:191], v[116:119]
	v_mfma_f32_16x16x32_bf16 v[112:115], v[180:183], v[188:191], v[112:115]
	v_mfma_f32_16x16x32_bf16 v[100:103], v[172:175], v[196:199], v[100:103]
	v_mfma_f32_16x16x32_bf16 v[96:99], v[180:183], v[196:199], v[96:99]
	v_mfma_f32_16x16x32_bf16 v[84:87], v[172:175], v[204:207], v[84:87]
	v_mfma_f32_16x16x32_bf16 v[80:83], v[180:183], v[204:207], v[80:83]
	v_mfma_f32_16x16x32_bf16 v[68:71], v[172:175], v[214:217], v[68:71]
	v_mfma_f32_16x16x32_bf16 v[64:67], v[180:183], v[214:217], v[64:67]
	s_barrier
	s_add_i32 s58, s47, s36
	v_lshl_add_u64 v[218:219], s[26:27], 0, v[130:131]
	s_mov_b32 m0, s58
	ds_read_b128 v[184:187], v154 offset:16384
	ds_read_b128 v[188:191], v154 offset:17408
	ds_read_b128 v[192:195], v154 offset:18432
	ds_read_b128 v[196:199], v154 offset:19456
	ds_read_b128 v[200:203], v154 offset:20480
	ds_read_b128 v[204:207], v154 offset:21504
	ds_read_b128 v[210:213], v154 offset:22528
	ds_read_b128 v[214:217], v154 offset:23552
	global_load_lds_dwordx4 v[218:219], off
	s_add_i32 m0, s58, 0x2000
	s_add_u32 s58, s26, 0xb0000
	v_lshl_add_u64 v[220:221], s[26:27], 0, v[134:135]
	s_addc_u32 s59, s27, 0
	s_add_i32 s60, s48, s36
	global_load_lds_dwordx4 v[220:221], off
	v_lshl_add_u64 v[222:223], s[58:59], 0, v[130:131]
	s_mov_b32 m0, s60
	v_lshl_add_u64 v[224:225], s[28:29], 0, v[132:133]
	global_load_lds_dwordx4 v[222:223], off
	v_lshl_add_u64 v[222:223], s[58:59], 0, v[134:135]
	s_add_i32 m0, s60, 0x2000
	s_nop 0
	global_load_lds_dwordx4 v[222:223], off
	v_lshl_add_u64 v[222:223], s[28:29], 0, v[128:129]
	s_mov_b32 m0, s37
	s_nop 0
	global_load_lds_dwordx4 v[222:223], off
	s_mov_b32 m0, s38
	s_nop 0
	global_load_lds_dwordx4 v[224:225], off
	s_waitcnt vmcnt(8)
	s_waitcnt lgkmcnt(0)
	s_barrier
; #define PG8_STAGE(bufoff, gbase, voff) do { _Pragma("unroll") for (int _i = 0; _i < 2; ++_i) \
;         __builtin_amdgcn_global_load_lds((const unsigned*)((const char*)(gbase) + (voff)[_i]), (PG8_LAS unsigned*)(lds + (bufoff) + ldsw + _i * 8192), 16, 0, 0); } while (0)
; #define PG8_LDA(dst, b, h) do { _Pragma("unroll") for (int m = 0; m < 4; ++m) _Pragma("unroll") for (int k = 0; k < 2; ++k) dst[m][k] = *(const PG8_LAS bf16x8*)(lds + PG8_SA(b, h) + aoff + m * 2048 + k * 1024); } while (0)
; #define PG8_LDB(dst, b, h) do { _Pragma("unroll") for (int n = 0; n < 2; ++n) _Pragma("unroll") for (int k = 0; k < 2; ++k) dst[n][k] = *(const PG8_LAS bf16x8*)(lds + PG8_SB(b, h) + boff + n * 2048 + k * 1024); } while (0)
; #define PG8_MMA(ai, bj, At, Bt) do { __builtin_amdgcn_s_setprio(1); _Pragma("unroll") for (int m = 0; m < 4; ++m) _Pragma("unroll") for (int n = 0; n < 2; ++n) _Pragma("unroll") for (int k = 0; k < 2; ++k) \
;         acc[ai][bj][m][n] = __builtin_amdgcn_mfma_f32_16x16x32_bf16(Bt[n][k], At[m][k], acc[ai][bj][m][n], 0, 0, 0); __builtin_amdgcn_s_setprio(0); } while (0)
; #define PG8_WAIT_V(n) asm volatile("s_waitcnt vmcnt(" #n ")" ::: "memory")
; #define PG8_WAIT_L(n) asm volatile("s_waitcnt lgkmcnt(" #n ")" ::: "memory")
; #define PG8_BAR __builtin_amdgcn_s_barrier()
; #define PG8_SCHED __builtin_amdgcn_sched_barrier(0)
; template <class Epi, class Sched, bool ALIGN_EPI = false, bool SP2 = false>
; __device__ __forceinline__ void gemm_phase(PG8_LAS unsigned char* lds, const Gemm g, const Sched& S, const Epi& E) {
;     ...
;             PG8_WAIT_V(8); PG8_WAIT_L(0); PG8_BAR; PG8_MMA(1, 0, At, B0); PG8_MMA(1, 1, At, B1); PG8_BAR; PG8_SCHED;
;             PG8_LDB(B0, 1, 0); PG8_LDB(B1, 1, 1); PG8_SCHED; PG8_LDA(At, 1, 0); PG8_STAGE(PG8_SA(0, 1), a2 + hstep, voffA);
;             PG8_WAIT_V(8); PG8_WAIT_L(0); PG8_BAR; PG8_MMA(0, 0, At, B0); PG8_MMA(0, 1, At, B1); PG8_BAR; PG8_SCHED;
	s_waitcnt lgkmcnt(0)
	v_mfma_f32_16x16x32_bf16 v[60:63], v[144:147], v[184:187], v[60:63]
	v_mfma_f32_16x16x32_bf16 v[56:59], v[160:163], v[184:187], v[56:59]
	v_mfma_f32_16x16x32_bf16 v[44:47], v[144:147], v[192:195], v[44:47]
	v_mfma_f32_16x16x32_bf16 v[40:43], v[160:163], v[192:195], v[40:43]
	v_mfma_f32_16x16x32_bf16 v[28:31], v[144:147], v[200:203], v[28:31]
	v_mfma_f32_16x16x32_bf16 v[24:27], v[160:163], v[200:203], v[24:27]
	v_mfma_f32_16x16x32_bf16 v[12:15], v[144:147], v[210:213], v[12:15]
	v_mfma_f32_16x16x32_bf16 v[8:11], v[160:163], v[210:213], v[8:11]
	v_mfma_f32_16x16x32_bf16 v[60:63], v[156:159], v[188:191], v[60:63]
	v_mfma_f32_16x16x32_bf16 v[56:59], v[164:167], v[188:191], v[56:59]
	v_mfma_f32_16x16x32_bf16 v[44:47], v[156:159], v[196:199], v[44:47]
	v_mfma_f32_16x16x32_bf16 v[40:43], v[164:167], v[196:199], v[40:43]
	v_mfma_f32_16x16x32_bf16 v[28:31], v[156:159], v[204:207], v[28:31]
	v_mfma_f32_16x16x32_bf16 v[24:27], v[164:167], v[204:207], v[24:27]
	v_mfma_f32_16x16x32_bf16 v[12:15], v[156:159], v[214:217], v[12:15]
	v_mfma_f32_16x16x32_bf16 v[8:11], v[164:167], v[214:217], v[8:11]
	v_mfma_f32_16x16x32_bf16 v[52:55], v[168:171], v[184:187], v[52:55]
	v_mfma_f32_16x16x32_bf16 v[48:51], v[176:179], v[184:187], v[48:51]
	v_mfma_f32_16x16x32_bf16 v[36:39], v[168:171], v[192:195], v[36:39]
	v_mfma_f32_16x16x32_bf16 v[32:35], v[176:179], v[192:195], v[32:35]
	v_mfma_f32_16x16x32_bf16 v[20:23], v[168:171], v[200:203], v[20:23]
	v_mfma_f32_16x16x32_bf16 v[16:19], v[176:179], v[200:203], v[16:19]
	v_mfma_f32_16x16x32_bf16 v[4:7], v[168:171], v[210:213], v[4:7]
	v_mfma_f32_16x16x32_bf16 v[0:3], v[176:179], v[210:213], v[0:3]
	v_mfma_f32_16x16x32_bf16 v[52:55], v[172:175], v[188:191], v[52:55]
	v_mfma_f32_16x16x32_bf16 v[48:51], v[180:183], v[188:191], v[48:51]
	v_mfma_f32_16x16x32_bf16 v[36:39], v[172:175], v[196:199], v[36:39]
	v_mfma_f32_16x16x32_bf16 v[32:35], v[180:183], v[196:199], v[32:35]
	v_mfma_f32_16x16x32_bf16 v[20:23], v[172:175], v[204:207], v[20:23]
	v_mfma_f32_16x16x32_bf16 v[16:19], v[180:183], v[204:207], v[16:19]
	v_mfma_f32_16x16x32_bf16 v[4:7], v[172:175], v[214:217], v[4:7]
	v_mfma_f32_16x16x32_bf16 v[0:3], v[180:183], v[214:217], v[0:3]
	s_barrier
	s_add_i32 s58, 0, 0x18000
	s_add_i32 s59, 0, 0x1c000
	v_add_u32_e32 v164, s58, v150
	v_add_u32_e32 v180, s59, v150
	ds_read_b128 v[144:147], v164
	ds_read_b128 v[156:159], v164 offset:1024
	ds_read_b128 v[160:163], v164 offset:2048
	ds_read_b128 v[164:167], v164 offset:3072
	ds_read_b128 v[168:171], v180
	ds_read_b128 v[172:175], v180 offset:1024
	ds_read_b128 v[176:179], v180 offset:2048
	ds_read_b128 v[180:183], v180 offset:3072
	s_add_u32 s28, s28, 0xb0000
	s_addc_u32 s29, s29, 0
	s_mov_b32 m0, s39
	v_lshl_add_u64 v[226:227], s[28:29], 0, v[128:129]
	ds_read_b128 v[184:187], v154 offset:32768
	ds_read_b128 v[188:191], v154 offset:33792
	ds_read_b128 v[192:195], v154 offset:34816
	ds_read_b128 v[196:199], v154 offset:35840
	ds_read_b128 v[200:203], v154 offset:36864
	ds_read_b128 v[204:207], v154 offset:37888
	ds_read_b128 v[210:213], v154 offset:38912
	ds_read_b128 v[214:217], v154 offset:39936
	global_load_lds_dwordx4 v[226:227], off
	v_lshl_add_u64 v[226:227], s[28:29], 0, v[132:133]
	s_mov_b32 m0, s40
	s_nop 0
	global_load_lds_dwordx4 v[226:227], off
	s_waitcnt vmcnt(8)
	s_waitcnt lgkmcnt(0)
	s_barrier
	s_waitcnt lgkmcnt(0)
	v_mfma_f32_16x16x32_bf16 v[124:127], v[144:147], v[184:187], v[124:127]
	v_mfma_f32_16x16x32_bf16 v[120:123], v[160:163], v[184:187], v[120:123]
	v_mfma_f32_16x16x32_bf16 v[108:111], v[144:147], v[192:195], v[108:111]
	v_mfma_f32_16x16x32_bf16 v[104:107], v[160:163], v[192:195], v[104:107]
	v_mfma_f32_16x16x32_bf16 v[92:95], v[144:147], v[200:203], v[92:95]
	v_mfma_f32_16x16x32_bf16 v[88:91], v[160:163], v[200:203], v[88:91]
	v_mfma_f32_16x16x32_bf16 v[76:79], v[144:147], v[210:213], v[76:79]
	v_mfma_f32_16x16x32_bf16 v[72:75], v[160:163], v[210:213], v[72:75]
	v_mfma_f32_16x16x32_bf16 v[124:127], v[156:159], v[188:191], v[124:127]
	v_mfma_f32_16x16x32_bf16 v[120:123], v[164:167], v[188:191], v[120:123]
	v_mfma_f32_16x16x32_bf16 v[108:111], v[156:159], v[196:199], v[108:111]
	v_mfma_f32_16x16x32_bf16 v[104:107], v[164:167], v[196:199], v[104:107]
	v_mfma_f32_16x16x32_bf16 v[92:95], v[156:159], v[204:207], v[92:95]
	v_mfma_f32_16x16x32_bf16 v[88:91], v[164:167], v[204:207], v[88:91]
	v_mfma_f32_16x16x32_bf16 v[76:79], v[156:159], v[214:217], v[76:79]
	v_mfma_f32_16x16x32_bf16 v[72:75], v[164:167], v[214:217], v[72:75]
	v_mfma_f32_16x16x32_bf16 v[116:119], v[168:171], v[184:187], v[116:119]
	v_mfma_f32_16x16x32_bf16 v[112:115], v[176:179], v[184:187], v[112:115]
	v_mfma_f32_16x16x32_bf16 v[100:103], v[168:171], v[192:195], v[100:103]
	v_mfma_f32_16x16x32_bf16 v[96:99], v[176:179], v[192:195], v[96:99]
	v_mfma_f32_16x16x32_bf16 v[84:87], v[168:171], v[200:203], v[84:87]
	v_mfma_f32_16x16x32_bf16 v[80:83], v[176:179], v[200:203], v[80:83]
	v_mfma_f32_16x16x32_bf16 v[68:71], v[168:171], v[210:213], v[68:71]
	v_mfma_f32_16x16x32_bf16 v[64:67], v[176:179], v[210:213], v[64:67]
	v_mfma_f32_16x16x32_bf16 v[116:119], v[172:175], v[188:191], v[116:119]
	v_mfma_f32_16x16x32_bf16 v[112:115], v[180:183], v[188:191], v[112:115]
	v_mfma_f32_16x16x32_bf16 v[100:103], v[172:175], v[196:199], v[100:103]
	v_mfma_f32_16x16x32_bf16 v[96:99], v[180:183], v[196:199], v[96:99]
	v_mfma_f32_16x16x32_bf16 v[84:87], v[172:175], v[204:207], v[84:87]
	v_mfma_f32_16x16x32_bf16 v[80:83], v[180:183], v[204:207], v[80:83]
	v_mfma_f32_16x16x32_bf16 v[68:71], v[172:175], v[214:217], v[68:71]
	v_mfma_f32_16x16x32_bf16 v[64:67], v[180:183], v[214:217], v[64:67]
	s_barrier
; #define PG8_STAGE(bufoff, gbase, voff) do { _Pragma("unroll") for (int _i = 0; _i < 2; ++_i) \
;         __builtin_amdgcn_global_load_lds((const unsigned*)((const char*)(gbase) + (voff)[_i]), (PG8_LAS unsigned*)(lds + (bufoff) + ldsw + _i * 8192), 16, 0, 0); } while (0)
; #define PG8_LDA(dst, b, h) do { _Pragma("unroll") for (int m = 0; m < 4; ++m) _Pragma("unroll") for (int k = 0; k < 2; ++k) dst[m][k] = *(const PG8_LAS bf16x8*)(lds + PG8_SA(b, h) + aoff + m * 2048 + k * 1024); } while (0)
; #define PG8_MMA(ai, bj, At, Bt) do { __builtin_amdgcn_s_setprio(1); _Pragma("unroll") for (int m = 0; m < 4; ++m) _Pragma("unroll") for (int n = 0; n < 2; ++n) _Pragma("unroll") for (int k = 0; k < 2; ++k) \
;         acc[ai][bj][m][n] = __builtin_amdgcn_mfma_f32_16x16x32_bf16(Bt[n][k], At[m][k], acc[ai][bj][m][n], 0, 0, 0); __builtin_amdgcn_s_setprio(0); } while (0)
; #define PG8_WAIT_V(n) asm volatile("s_waitcnt vmcnt(" #n ")" ::: "memory")
; #define PG8_WAIT_L(n) asm volatile("s_waitcnt lgkmcnt(" #n ")" ::: "memory")
; #define PG8_BAR __builtin_amdgcn_s_barrier()
; #define PG8_SCHED __builtin_amdgcn_sched_barrier(0)
; template <class Epi, class Sched, bool ALIGN_EPI = false, bool SP2 = false>
; __device__ __forceinline__ void gemm_phase(PG8_LAS unsigned char* lds, const Gemm g, const Sched& S, const Epi& E) {
;     ...
;         for (int t = 0; t < nt; t += 2) {
;             const bool last = (t == nt - 2);
;             const char* a1 = cA + (size_t)(t + 1) * kstep;
;             const char* a2 = last ? nA : cA + (size_t)(t + 2) * kstep; const char* b2 = last ? nB : cB + (size_t)(t + 2) * kstep;
;             const char* a3 = a2 + kstep; const char* b3 = b2 + kstep;
;             if (last && has_next) S.a_ready(nxt);
;     ...
;             PG8_LDA(At, 1, 1); PG8_STAGE(PG8_SB(1, 0), b3, voffB); PG8_STAGE(PG8_SB(1, 1), b3 + hstep, voffB); PG8_STAGE(PG8_SA(1, 0), a3, voffA);
;             PG8_WAIT_V(8); PG8_WAIT_L(0); PG8_BAR; PG8_MMA(1, 0, At, B0); PG8_MMA(1, 1, At, B1); PG8_BAR; PG8_SCHED;
	s_add_i32 s28, s58, s36
	v_lshl_add_u64 v[218:219], v[218:219], 0, s[14:15]
	s_mov_b32 m0, s28
	ds_read_b128 v[184:187], v154 offset:49152
	ds_read_b128 v[188:191], v154 offset:50176
	ds_read_b128 v[192:195], v154 offset:51200
	ds_read_b128 v[196:199], v154 offset:52224
	ds_read_b128 v[200:203], v154 offset:53248
	ds_read_b128 v[204:207], v154 offset:54272
	ds_read_b128 v[210:213], v154 offset:55296
	ds_read_b128 v[214:217], v154 offset:56320
	global_load_lds_dwordx4 v[218:219], off
	s_add_i32 m0, s28, 0x2000
	s_add_u32 s26, s26, 0xb0080
	v_lshl_add_u64 v[218:219], v[220:221], 0, s[14:15]
	s_addc_u32 s27, s27, 0
	s_add_i32 s28, s59, s36
	global_load_lds_dwordx4 v[218:219], off
	v_lshl_add_u64 v[218:219], s[26:27], 0, v[130:131]
	s_mov_b32 m0, s28
	s_nop 0
	global_load_lds_dwordx4 v[218:219], off
	v_lshl_add_u64 v[218:219], s[26:27], 0, v[134:135]
	s_add_i32 m0, s28, 0x2000
	s_nop 0
	global_load_lds_dwordx4 v[218:219], off
	v_lshl_add_u64 v[218:219], v[222:223], 0, s[14:15]
	s_mov_b32 m0, s42
	s_nop 0
	global_load_lds_dwordx4 v[218:219], off
	v_lshl_add_u64 v[218:219], v[224:225], 0, s[14:15]
	s_mov_b32 m0, s43
	s_nop 0
	global_load_lds_dwordx4 v[218:219], off
	s_waitcnt vmcnt(8)
	s_waitcnt lgkmcnt(0)
	s_barrier
	s_waitcnt lgkmcnt(0)
	v_mfma_f32_16x16x32_bf16 v[60:63], v[144:147], v[184:187], v[60:63]
	v_mfma_f32_16x16x32_bf16 v[56:59], v[160:163], v[184:187], v[56:59]
	v_mfma_f32_16x16x32_bf16 v[44:47], v[144:147], v[192:195], v[44:47]
	v_mfma_f32_16x16x32_bf16 v[40:43], v[160:163], v[192:195], v[40:43]
	v_mfma_f32_16x16x32_bf16 v[28:31], v[144:147], v[200:203], v[28:31]
	v_mfma_f32_16x16x32_bf16 v[24:27], v[160:163], v[200:203], v[24:27]
	v_mfma_f32_16x16x32_bf16 v[12:15], v[144:147], v[210:213], v[12:15]
	v_mfma_f32_16x16x32_bf16 v[8:11], v[160:163], v[210:213], v[8:11]
	v_mfma_f32_16x16x32_bf16 v[60:63], v[156:159], v[188:191], v[60:63]
	v_mfma_f32_16x16x32_bf16 v[56:59], v[164:167], v[188:191], v[56:59]
	v_mfma_f32_16x16x32_bf16 v[44:47], v[156:159], v[196:199], v[44:47]
	v_mfma_f32_16x16x32_bf16 v[40:43], v[164:167], v[196:199], v[40:43]
	v_mfma_f32_16x16x32_bf16 v[28:31], v[156:159], v[204:207], v[28:31]
	v_mfma_f32_16x16x32_bf16 v[24:27], v[164:167], v[204:207], v[24:27]
	v_mfma_f32_16x16x32_bf16 v[12:15], v[156:159], v[214:217], v[12:15]
	v_mfma_f32_16x16x32_bf16 v[8:11], v[164:167], v[214:217], v[8:11]
	v_mfma_f32_16x16x32_bf16 v[52:55], v[168:171], v[184:187], v[52:55]
	v_mfma_f32_16x16x32_bf16 v[48:51], v[176:179], v[184:187], v[48:51]
	v_mfma_f32_16x16x32_bf16 v[36:39], v[168:171], v[192:195], v[36:39]
	v_mfma_f32_16x16x32_bf16 v[32:35], v[176:179], v[192:195], v[32:35]
	v_mfma_f32_16x16x32_bf16 v[20:23], v[168:171], v[200:203], v[20:23]
	v_mfma_f32_16x16x32_bf16 v[16:19], v[176:179], v[200:203], v[16:19]
	v_mfma_f32_16x16x32_bf16 v[4:7], v[168:171], v[210:213], v[4:7]
	v_mfma_f32_16x16x32_bf16 v[0:3], v[176:179], v[210:213], v[0:3]
	v_mfma_f32_16x16x32_bf16 v[52:55], v[172:175], v[188:191], v[52:55]
	v_mfma_f32_16x16x32_bf16 v[48:51], v[180:183], v[188:191], v[48:51]
	v_mfma_f32_16x16x32_bf16 v[36:39], v[172:175], v[196:199], v[36:39]
	v_mfma_f32_16x16x32_bf16 v[32:35], v[180:183], v[196:199], v[32:35]
	v_mfma_f32_16x16x32_bf16 v[20:23], v[172:175], v[204:207], v[20:23]
	v_mfma_f32_16x16x32_bf16 v[16:19], v[180:183], v[204:207], v[16:19]
	v_mfma_f32_16x16x32_bf16 v[4:7], v[172:175], v[214:217], v[4:7]
	v_mfma_f32_16x16x32_bf16 v[0:3], v[180:183], v[214:217], v[0:3]
	s_barrier
	s_add_i32 s57, s57, 2
	s_add_u32 s24, s24, 0x100
	s_addc_u32 s25, s25, 0
	s_add_u32 s53, s53, 0x100
	s_addc_u32 s56, s56, 0
	s_cmp_gt_u32 s57, 41
	s_cbranch_scc0 .LBB0_314
	s_and_b64 vcc, exec, s[16:17]
	s_cbranch_vccz .LBB0_317
	s_barrier

; #define PG8_STAGE(bufoff, gbase, voff) do { _Pragma("unroll") for (int _i = 0; _i < 2; ++_i) \
;         __builtin_amdgcn_global_load_lds((const unsigned*)((const char*)(gbase) + (voff)[_i]), (PG8_LAS unsigned*)(lds + (bufoff) + ldsw + _i * 8192), 16, 0, 0); } while (0)
; #define PG8_LDA(dst, b, h) do { _Pragma("unroll") for (int m = 0; m < 4; ++m) _Pragma("unroll") for (int k = 0; k < 2; ++k) dst[m][k] = *(const PG8_LAS bf16x8*)(lds + PG8_SA(b, h) + aoff + m * 2048 + k * 1024); } while (0)
; #define PG8_LDB(dst, b, h) do { _Pragma("unroll") for (int n = 0; n < 2; ++n) _Pragma("unroll") for (int k = 0; k < 2; ++k) dst[n][k] = *(const PG8_LAS bf16x8*)(lds + PG8_SB(b, h) + boff + n * 2048 + k * 1024); } while (0)
; #define PG8_MMA(ai, bj, At, Bt) do { __builtin_amdgcn_s_setprio(1); _Pragma("unroll") for (int m = 0; m < 4; ++m) _Pragma("unroll") for (int n = 0; n < 2; ++n) _Pragma("unroll") for (int k = 0; k < 2; ++k) \
;         acc[ai][bj][m][n] = __builtin_amdgcn_mfma_f32_16x16x32_bf16(Bt[n][k], At[m][k], acc[ai][bj][m][n], 0, 0, 0); __builtin_amdgcn_s_setprio(0); } while (0)
; #define PG8_WAIT_V(n) asm volatile("s_waitcnt vmcnt(" #n ")" ::: "memory")
; #define PG8_WAIT_L(n) asm volatile("s_waitcnt lgkmcnt(" #n ")" ::: "memory")
; #define PG8_BAR __builtin_amdgcn_s_barrier()
; #define PG8_SCHED __builtin_amdgcn_sched_barrier(0)
; template <class Epi, class Sched, bool ALIGN_EPI = false, bool SP2 = false>
; __device__ __forceinline__ void gemm_phase(PG8_LAS unsigned char* lds, const Gemm g, const Sched& S, const Epi& E) {
;     ...
;             PG8_LDB(B0, 0, 0); PG8_LDB(B1, 0, 1); PG8_SCHED; PG8_LDA(At, 0, 0); PG8_STAGE(PG8_SA(1, 1), a1 + hstep, voffA);
;             PG8_WAIT_V(8); PG8_WAIT_L(0); PG8_BAR; PG8_MMA(0, 0, At, B0); PG8_MMA(0, 1, At, B1); PG8_BAR; PG8_SCHED;
;             PG8_LDA(At, 0, 1); PG8_STAGE(PG8_SB(0, 0), b2, voffB); PG8_STAGE(PG8_SB(0, 1), b2 + hstep, voffB); PG8_STAGE(PG8_SA(0, 0), a2, voffA);
;             PG8_WAIT_V(8); PG8_WAIT_L(0); PG8_BAR; PG8_MMA(1, 0, At, B0); PG8_MMA(1, 1, At, B1); PG8_BAR; PG8_SCHED;
.LBB0_410:
	ds_read_b128 v[144:147], v155
	ds_read_b128 v[160:163], v155 offset:1024
	ds_read_b128 v[164:167], v155 offset:2048
	ds_read_b128 v[168:171], v155 offset:3072
	ds_read_b128 v[172:175], v156
	ds_read_b128 v[176:179], v156 offset:1024
	ds_read_b128 v[180:183], v156 offset:2048
	ds_read_b128 v[184:187], v156 offset:3072
	s_add_u32 s22, s18, 0xfffc0080
	s_addc_u32 s23, s19, -1
	s_cmp_eq_u32 s50, 12
	s_cselect_b32 s25, s11, s23
	s_cselect_b32 s24, s46, s22
	s_cselect_b32 s23, s9, s49
	s_cselect_b32 s22, s47, s48
	v_lshl_add_u64 v[148:149], s[18:19], 0, v[136:137]
	s_add_i32 m0, s17, 0xc000
	ds_read_b128 v[188:191], v157
	ds_read_b128 v[192:195], v157 offset:1024
	ds_read_b128 v[196:199], v157 offset:2048
	ds_read_b128 v[200:203], v157 offset:3072
	ds_read_b128 v[204:207], v157 offset:4096
	ds_read_b128 v[210:213], v157 offset:5120
	ds_read_b128 v[214:217], v157 offset:6144
	ds_read_b128 v[218:221], v157 offset:7168
	global_load_lds_dwordx4 v[148:149], off
	v_lshl_add_u64 v[148:149], s[18:19], 0, v[138:139]
	s_add_i32 m0, s17, 0xe000
	s_nop 0
	global_load_lds_dwordx4 v[148:149], off
	s_waitcnt vmcnt(8)
	s_waitcnt lgkmcnt(0)
	s_barrier
	s_waitcnt lgkmcnt(0)
	v_mfma_f32_16x16x32_bf16 v[124:127], v[144:147], v[188:191], v[124:127]
	v_mfma_f32_16x16x32_bf16 v[120:123], v[164:167], v[188:191], v[120:123]
	v_mfma_f32_16x16x32_bf16 v[108:111], v[144:147], v[196:199], v[108:111]
	v_mfma_f32_16x16x32_bf16 v[104:107], v[164:167], v[196:199], v[104:107]
	v_mfma_f32_16x16x32_bf16 v[92:95], v[144:147], v[204:207], v[92:95]
	v_mfma_f32_16x16x32_bf16 v[88:91], v[164:167], v[204:207], v[88:91]
	v_mfma_f32_16x16x32_bf16 v[84:87], v[144:147], v[214:217], v[84:87]
	v_mfma_f32_16x16x32_bf16 v[76:79], v[164:167], v[214:217], v[76:79]
	v_mfma_f32_16x16x32_bf16 v[124:127], v[160:163], v[192:195], v[124:127]
	v_mfma_f32_16x16x32_bf16 v[120:123], v[168:171], v[192:195], v[120:123]
	v_mfma_f32_16x16x32_bf16 v[108:111], v[160:163], v[200:203], v[108:111]
	v_mfma_f32_16x16x32_bf16 v[104:107], v[168:171], v[200:203], v[104:107]
	v_mfma_f32_16x16x32_bf16 v[92:95], v[160:163], v[210:213], v[92:95]
	v_mfma_f32_16x16x32_bf16 v[88:91], v[168:171], v[210:213], v[88:91]
	v_mfma_f32_16x16x32_bf16 v[84:87], v[160:163], v[218:221], v[84:87]
	v_mfma_f32_16x16x32_bf16 v[76:79], v[168:171], v[218:221], v[76:79]
	v_mfma_f32_16x16x32_bf16 v[116:119], v[172:175], v[188:191], v[116:119]
	v_mfma_f32_16x16x32_bf16 v[112:115], v[180:183], v[188:191], v[112:115]
	v_mfma_f32_16x16x32_bf16 v[100:103], v[172:175], v[196:199], v[100:103]
	v_mfma_f32_16x16x32_bf16 v[96:99], v[180:183], v[196:199], v[96:99]
	v_mfma_f32_16x16x32_bf16 v[80:83], v[172:175], v[204:207], v[80:83]
	v_mfma_f32_16x16x32_bf16 v[72:75], v[180:183], v[204:207], v[72:75]
	v_mfma_f32_16x16x32_bf16 v[68:71], v[172:175], v[214:217], v[68:71]
	v_mfma_f32_16x16x32_bf16 v[64:67], v[180:183], v[214:217], v[64:67]
	v_mfma_f32_16x16x32_bf16 v[116:119], v[176:179], v[192:195], v[116:119]
	v_mfma_f32_16x16x32_bf16 v[112:115], v[184:187], v[192:195], v[112:115]
	v_mfma_f32_16x16x32_bf16 v[100:103], v[176:179], v[200:203], v[100:103]
	v_mfma_f32_16x16x32_bf16 v[96:99], v[184:187], v[200:203], v[96:99]
	v_mfma_f32_16x16x32_bf16 v[80:83], v[176:179], v[210:213], v[80:83]
	v_mfma_f32_16x16x32_bf16 v[72:75], v[184:187], v[210:213], v[72:75]
	v_mfma_f32_16x16x32_bf16 v[68:71], v[176:179], v[218:221], v[68:71]
	v_mfma_f32_16x16x32_bf16 v[64:67], v[184:187], v[218:221], v[64:67]
	s_barrier
	s_add_i32 s51, s43, s30
	v_lshl_add_u64 v[148:149], s[22:23], 0, v[130:131]
	s_mov_b32 m0, s51
	ds_read_b128 v[188:191], v157 offset:16384
	ds_read_b128 v[192:195], v157 offset:17408
	ds_read_b128 v[196:199], v157 offset:18432
	ds_read_b128 v[200:203], v157 offset:19456
	ds_read_b128 v[204:207], v157 offset:20480
	ds_read_b128 v[210:213], v157 offset:21504
	ds_read_b128 v[214:217], v157 offset:22528
	ds_read_b128 v[218:221], v157 offset:23552
	global_load_lds_dwordx4 v[148:149], off
	s_add_i32 m0, s51, 0x2000
	s_add_u32 s52, s22, 0x40000
	v_lshl_add_u64 v[222:223], s[22:23], 0, v[134:135]
	s_addc_u32 s53, s23, 0
	s_add_i32 s51, s44, s30
	global_load_lds_dwordx4 v[222:223], off
	v_lshl_add_u64 v[224:225], s[52:53], 0, v[130:131]
	s_mov_b32 m0, s51
	v_lshl_add_u64 v[226:227], s[24:25], 0, v[132:133]
	global_load_lds_dwordx4 v[224:225], off
	v_lshl_add_u64 v[224:225], s[52:53], 0, v[134:135]
	s_add_i32 m0, s51, 0x2000
	s_nop 0
	global_load_lds_dwordx4 v[224:225], off
	v_lshl_add_u64 v[224:225], s[24:25], 0, v[128:129]
	s_mov_b32 m0, s17
	s_nop 0
	global_load_lds_dwordx4 v[224:225], off
	s_mov_b32 m0, s35
	s_nop 0
	global_load_lds_dwordx4 v[226:227], off
	s_waitcnt vmcnt(8)
	s_waitcnt lgkmcnt(0)
	s_barrier
; #define PG8_STAGE(bufoff, gbase, voff) do { _Pragma("unroll") for (int _i = 0; _i < 2; ++_i) \
;         __builtin_amdgcn_global_load_lds((const unsigned*)((const char*)(gbase) + (voff)[_i]), (PG8_LAS unsigned*)(lds + (bufoff) + ldsw + _i * 8192), 16, 0, 0); } while (0)
; #define PG8_LDA(dst, b, h) do { _Pragma("unroll") for (int m = 0; m < 4; ++m) _Pragma("unroll") for (int k = 0; k < 2; ++k) dst[m][k] = *(const PG8_LAS bf16x8*)(lds + PG8_SA(b, h) + aoff + m * 2048 + k * 1024); } while (0)
; #define PG8_LDB(dst, b, h) do { _Pragma("unroll") for (int n = 0; n < 2; ++n) _Pragma("unroll") for (int k = 0; k < 2; ++k) dst[n][k] = *(const PG8_LAS bf16x8*)(lds + PG8_SB(b, h) + boff + n * 2048 + k * 1024); } while (0)
; #define PG8_MMA(ai, bj, At, Bt) do { __builtin_amdgcn_s_setprio(1); _Pragma("unroll") for (int m = 0; m < 4; ++m) _Pragma("unroll") for (int n = 0; n < 2; ++n) _Pragma("unroll") for (int k = 0; k < 2; ++k) \
;         acc[ai][bj][m][n] = __builtin_amdgcn_mfma_f32_16x16x32_bf16(Bt[n][k], At[m][k], acc[ai][bj][m][n], 0, 0, 0); __builtin_amdgcn_s_setprio(0); } while (0)
; #define PG8_WAIT_V(n) asm volatile("s_waitcnt vmcnt(" #n ")" ::: "memory")
; #define PG8_WAIT_L(n) asm volatile("s_waitcnt lgkmcnt(" #n ")" ::: "memory")
; #define PG8_BAR __builtin_amdgcn_s_barrier()
; #define PG8_SCHED __builtin_amdgcn_sched_barrier(0)
; template <class Epi, class Sched, bool ALIGN_EPI = false, bool SP2 = false>
; __device__ __forceinline__ void gemm_phase(PG8_LAS unsigned char* lds, const Gemm g, const Sched& S, const Epi& E) {
;     ...
;             PG8_WAIT_V(8); PG8_WAIT_L(0); PG8_BAR; PG8_MMA(1, 0, At, B0); PG8_MMA(1, 1, At, B1); PG8_BAR; PG8_SCHED;
;             PG8_LDB(B0, 1, 0); PG8_LDB(B1, 1, 1); PG8_SCHED; PG8_LDA(At, 1, 0); PG8_STAGE(PG8_SA(0, 1), a2 + hstep, voffA);
;             PG8_WAIT_V(8); PG8_WAIT_L(0); PG8_BAR; PG8_MMA(0, 0, At, B0); PG8_MMA(0, 1, At, B1); PG8_BAR; PG8_SCHED;
	s_waitcnt lgkmcnt(0)
	v_mfma_f32_16x16x32_bf16 v[60:63], v[144:147], v[188:191], v[60:63]
	v_mfma_f32_16x16x32_bf16 v[56:59], v[164:167], v[188:191], v[56:59]
	v_mfma_f32_16x16x32_bf16 v[44:47], v[144:147], v[196:199], v[44:47]
	v_mfma_f32_16x16x32_bf16 v[40:43], v[164:167], v[196:199], v[40:43]
	v_mfma_f32_16x16x32_bf16 v[28:31], v[144:147], v[204:207], v[28:31]
	v_mfma_f32_16x16x32_bf16 v[24:27], v[164:167], v[204:207], v[24:27]
	v_mfma_f32_16x16x32_bf16 v[12:15], v[144:147], v[214:217], v[12:15]
	v_mfma_f32_16x16x32_bf16 v[8:11], v[164:167], v[214:217], v[8:11]
	v_mfma_f32_16x16x32_bf16 v[60:63], v[160:163], v[192:195], v[60:63]
	v_mfma_f32_16x16x32_bf16 v[56:59], v[168:171], v[192:195], v[56:59]
	v_mfma_f32_16x16x32_bf16 v[44:47], v[160:163], v[200:203], v[44:47]
	v_mfma_f32_16x16x32_bf16 v[40:43], v[168:171], v[200:203], v[40:43]
	v_mfma_f32_16x16x32_bf16 v[28:31], v[160:163], v[210:213], v[28:31]
	v_mfma_f32_16x16x32_bf16 v[24:27], v[168:171], v[210:213], v[24:27]
	v_mfma_f32_16x16x32_bf16 v[12:15], v[160:163], v[218:221], v[12:15]
	v_mfma_f32_16x16x32_bf16 v[8:11], v[168:171], v[218:221], v[8:11]
	v_mfma_f32_16x16x32_bf16 v[52:55], v[172:175], v[188:191], v[52:55]
	v_mfma_f32_16x16x32_bf16 v[48:51], v[180:183], v[188:191], v[48:51]
	v_mfma_f32_16x16x32_bf16 v[36:39], v[172:175], v[196:199], v[36:39]
	v_mfma_f32_16x16x32_bf16 v[32:35], v[180:183], v[196:199], v[32:35]
	v_mfma_f32_16x16x32_bf16 v[20:23], v[172:175], v[204:207], v[20:23]
	v_mfma_f32_16x16x32_bf16 v[16:19], v[180:183], v[204:207], v[16:19]
	v_mfma_f32_16x16x32_bf16 v[4:7], v[172:175], v[214:217], v[4:7]
	v_mfma_f32_16x16x32_bf16 v[0:3], v[180:183], v[214:217], v[0:3]
	v_mfma_f32_16x16x32_bf16 v[52:55], v[176:179], v[192:195], v[52:55]
	v_mfma_f32_16x16x32_bf16 v[48:51], v[184:187], v[192:195], v[48:51]
	v_mfma_f32_16x16x32_bf16 v[36:39], v[176:179], v[200:203], v[36:39]
	v_mfma_f32_16x16x32_bf16 v[32:35], v[184:187], v[200:203], v[32:35]
	v_mfma_f32_16x16x32_bf16 v[20:23], v[176:179], v[210:213], v[20:23]
	v_mfma_f32_16x16x32_bf16 v[16:19], v[184:187], v[210:213], v[16:19]
	v_mfma_f32_16x16x32_bf16 v[4:7], v[176:179], v[218:221], v[4:7]
	v_mfma_f32_16x16x32_bf16 v[0:3], v[184:187], v[218:221], v[0:3]
	s_barrier
	s_add_i32 s51, 0, 0x18000
	v_add_u32_e32 v159, s51, v153
	s_add_i32 s52, 0, 0x1c000
	ds_read_b128 v[144:147], v159
	ds_read_b128 v[160:163], v159 offset:1024
	ds_read_b128 v[164:167], v159 offset:2048
	ds_read_b128 v[168:171], v159 offset:3072
	v_add_u32_e32 v159, s52, v153
	ds_read_b128 v[172:175], v159
	ds_read_b128 v[176:179], v159 offset:1024
	ds_read_b128 v[180:183], v159 offset:2048
	ds_read_b128 v[184:187], v159 offset:3072
	s_add_u32 s24, s24, 0x40000
	s_addc_u32 s25, s25, 0
	s_mov_b32 m0, s36
	v_lshl_add_u64 v[228:229], s[24:25], 0, v[128:129]
	ds_read_b128 v[188:191], v157 offset:32768
	ds_read_b128 v[192:195], v157 offset:33792
	ds_read_b128 v[196:199], v157 offset:34816
	ds_read_b128 v[200:203], v157 offset:35840
	ds_read_b128 v[204:207], v157 offset:36864
	ds_read_b128 v[210:213], v157 offset:37888
	ds_read_b128 v[214:217], v157 offset:38912
	ds_read_b128 v[218:221], v157 offset:39936
	global_load_lds_dwordx4 v[228:229], off
	v_lshl_add_u64 v[228:229], s[24:25], 0, v[132:133]
	s_mov_b32 m0, s37
	s_nop 0
	global_load_lds_dwordx4 v[228:229], off
	s_waitcnt vmcnt(8)
	s_waitcnt lgkmcnt(0)
	s_barrier
	s_waitcnt lgkmcnt(0)
	v_mfma_f32_16x16x32_bf16 v[124:127], v[144:147], v[188:191], v[124:127]
	v_mfma_f32_16x16x32_bf16 v[120:123], v[164:167], v[188:191], v[120:123]
	v_mfma_f32_16x16x32_bf16 v[108:111], v[144:147], v[196:199], v[108:111]
	v_mfma_f32_16x16x32_bf16 v[104:107], v[164:167], v[196:199], v[104:107]
	v_mfma_f32_16x16x32_bf16 v[92:95], v[144:147], v[204:207], v[92:95]
	v_mfma_f32_16x16x32_bf16 v[88:91], v[164:167], v[204:207], v[88:91]
	v_mfma_f32_16x16x32_bf16 v[84:87], v[144:147], v[214:217], v[84:87]
	v_mfma_f32_16x16x32_bf16 v[76:79], v[164:167], v[214:217], v[76:79]
	v_mfma_f32_16x16x32_bf16 v[124:127], v[160:163], v[192:195], v[124:127]
	v_mfma_f32_16x16x32_bf16 v[120:123], v[168:171], v[192:195], v[120:123]
	v_mfma_f32_16x16x32_bf16 v[108:111], v[160:163], v[200:203], v[108:111]
	v_mfma_f32_16x16x32_bf16 v[104:107], v[168:171], v[200:203], v[104:107]
	v_mfma_f32_16x16x32_bf16 v[92:95], v[160:163], v[210:213], v[92:95]
	v_mfma_f32_16x16x32_bf16 v[88:91], v[168:171], v[210:213], v[88:91]
	v_mfma_f32_16x16x32_bf16 v[84:87], v[160:163], v[218:221], v[84:87]
	v_mfma_f32_16x16x32_bf16 v[76:79], v[168:171], v[218:221], v[76:79]
	v_mfma_f32_16x16x32_bf16 v[116:119], v[172:175], v[188:191], v[116:119]
	v_mfma_f32_16x16x32_bf16 v[112:115], v[180:183], v[188:191], v[112:115]
	v_mfma_f32_16x16x32_bf16 v[100:103], v[172:175], v[196:199], v[100:103]
	v_mfma_f32_16x16x32_bf16 v[96:99], v[180:183], v[196:199], v[96:99]
	v_mfma_f32_16x16x32_bf16 v[80:83], v[172:175], v[204:207], v[80:83]
	v_mfma_f32_16x16x32_bf16 v[72:75], v[180:183], v[204:207], v[72:75]
	v_mfma_f32_16x16x32_bf16 v[68:71], v[172:175], v[214:217], v[68:71]
	v_mfma_f32_16x16x32_bf16 v[64:67], v[180:183], v[214:217], v[64:67]
	v_mfma_f32_16x16x32_bf16 v[116:119], v[176:179], v[192:195], v[116:119]
	v_mfma_f32_16x16x32_bf16 v[112:115], v[184:187], v[192:195], v[112:115]
	v_mfma_f32_16x16x32_bf16 v[100:103], v[176:179], v[200:203], v[100:103]
	v_mfma_f32_16x16x32_bf16 v[96:99], v[184:187], v[200:203], v[96:99]
	v_mfma_f32_16x16x32_bf16 v[80:83], v[176:179], v[210:213], v[80:83]
	v_mfma_f32_16x16x32_bf16 v[72:75], v[184:187], v[210:213], v[72:75]
	v_mfma_f32_16x16x32_bf16 v[68:71], v[176:179], v[218:221], v[68:71]
	v_mfma_f32_16x16x32_bf16 v[64:67], v[184:187], v[218:221], v[64:67]
	s_barrier
; #define PG8_STAGE(bufoff, gbase, voff) do { _Pragma("unroll") for (int _i = 0; _i < 2; ++_i) \
;         __builtin_amdgcn_global_load_lds((const unsigned*)((const char*)(gbase) + (voff)[_i]), (PG8_LAS unsigned*)(lds + (bufoff) + ldsw + _i * 8192), 16, 0, 0); } while (0)
; #define PG8_LDA(dst, b, h) do { _Pragma("unroll") for (int m = 0; m < 4; ++m) _Pragma("unroll") for (int k = 0; k < 2; ++k) dst[m][k] = *(const PG8_LAS bf16x8*)(lds + PG8_SA(b, h) + aoff + m * 2048 + k * 1024); } while (0)
; #define PG8_MMA(ai, bj, At, Bt) do { __builtin_amdgcn_s_setprio(1); _Pragma("unroll") for (int m = 0; m < 4; ++m) _Pragma("unroll") for (int n = 0; n < 2; ++n) _Pragma("unroll") for (int k = 0; k < 2; ++k) \
;         acc[ai][bj][m][n] = __builtin_amdgcn_mfma_f32_16x16x32_bf16(Bt[n][k], At[m][k], acc[ai][bj][m][n], 0, 0, 0); __builtin_amdgcn_s_setprio(0); } while (0)
; #define PG8_WAIT_V(n) asm volatile("s_waitcnt vmcnt(" #n ")" ::: "memory")
; #define PG8_WAIT_L(n) asm volatile("s_waitcnt lgkmcnt(" #n ")" ::: "memory")
; #define PG8_BAR __builtin_amdgcn_s_barrier()
; #define PG8_SCHED __builtin_amdgcn_sched_barrier(0)
; template <class Epi, class Sched, bool ALIGN_EPI = false, bool SP2 = false>
; __device__ __forceinline__ void gemm_phase(PG8_LAS unsigned char* lds, const Gemm g, const Sched& S, const Epi& E) {
;     ...
;         for (int t = 0; t < nt; t += 2) {
;             const bool last = (t == nt - 2);
;             const char* a1 = cA + (size_t)(t + 1) * kstep;
;             const char* a2 = last ? nA : cA + (size_t)(t + 2) * kstep; const char* b2 = last ? nB : cB + (size_t)(t + 2) * kstep;
;             const char* a3 = a2 + kstep; const char* b3 = b2 + kstep;
;             if (last && has_next) S.a_ready(nxt);
;     ...
;             PG8_LDA(At, 1, 1); PG8_STAGE(PG8_SB(1, 0), b3, voffB); PG8_STAGE(PG8_SB(1, 1), b3 + hstep, voffB); PG8_STAGE(PG8_SA(1, 0), a3, voffA);
;             PG8_WAIT_V(8); PG8_WAIT_L(0); PG8_BAR; PG8_MMA(1, 0, At, B0); PG8_MMA(1, 1, At, B1); PG8_BAR; PG8_SCHED;
	s_add_i32 s24, s51, s30
	v_lshl_add_u64 v[148:149], v[148:149], 0, s[4:5]
	s_mov_b32 m0, s24
	ds_read_b128 v[188:191], v157 offset:49152
	ds_read_b128 v[192:195], v157 offset:50176
	ds_read_b128 v[196:199], v157 offset:51200
	ds_read_b128 v[200:203], v157 offset:52224
	ds_read_b128 v[204:207], v157 offset:53248
	ds_read_b128 v[210:213], v157 offset:54272
	ds_read_b128 v[214:217], v157 offset:55296
	ds_read_b128 v[218:221], v157 offset:56320
	global_load_lds_dwordx4 v[148:149], off
	s_add_i32 m0, s24, 0x2000
	s_add_u32 s22, s22, 0x40080
	v_lshl_add_u64 v[148:149], v[222:223], 0, s[4:5]
	s_addc_u32 s23, s23, 0
	s_add_i32 s24, s52, s30
	global_load_lds_dwordx4 v[148:149], off
	v_lshl_add_u64 v[148:149], s[22:23], 0, v[130:131]
	s_mov_b32 m0, s24
	s_nop 0
	global_load_lds_dwordx4 v[148:149], off
	v_lshl_add_u64 v[148:149], s[22:23], 0, v[134:135]
	s_add_i32 m0, s24, 0x2000
	s_nop 0
	global_load_lds_dwordx4 v[148:149], off
	v_lshl_add_u64 v[148:149], v[224:225], 0, s[4:5]
	s_mov_b32 m0, s40
	s_nop 0
	global_load_lds_dwordx4 v[148:149], off
	v_lshl_add_u64 v[148:149], v[226:227], 0, s[4:5]
	s_mov_b32 m0, s41
	s_nop 0
	global_load_lds_dwordx4 v[148:149], off
	s_waitcnt vmcnt(8)
	s_waitcnt lgkmcnt(0)
	s_barrier
	s_waitcnt lgkmcnt(0)
	v_mfma_f32_16x16x32_bf16 v[60:63], v[144:147], v[188:191], v[60:63]
	v_mfma_f32_16x16x32_bf16 v[56:59], v[164:167], v[188:191], v[56:59]
	v_mfma_f32_16x16x32_bf16 v[44:47], v[144:147], v[196:199], v[44:47]
	v_mfma_f32_16x16x32_bf16 v[40:43], v[164:167], v[196:199], v[40:43]
	v_mfma_f32_16x16x32_bf16 v[28:31], v[144:147], v[204:207], v[28:31]
	v_mfma_f32_16x16x32_bf16 v[24:27], v[164:167], v[204:207], v[24:27]
	v_mfma_f32_16x16x32_bf16 v[12:15], v[144:147], v[214:217], v[12:15]
	v_mfma_f32_16x16x32_bf16 v[8:11], v[164:167], v[214:217], v[8:11]
	v_mfma_f32_16x16x32_bf16 v[60:63], v[160:163], v[192:195], v[60:63]
	v_mfma_f32_16x16x32_bf16 v[56:59], v[168:171], v[192:195], v[56:59]
	v_mfma_f32_16x16x32_bf16 v[44:47], v[160:163], v[200:203], v[44:47]
	v_mfma_f32_16x16x32_bf16 v[40:43], v[168:171], v[200:203], v[40:43]
	v_mfma_f32_16x16x32_bf16 v[28:31], v[160:163], v[210:213], v[28:31]
	v_mfma_f32_16x16x32_bf16 v[24:27], v[168:171], v[210:213], v[24:27]
	v_mfma_f32_16x16x32_bf16 v[12:15], v[160:163], v[218:221], v[12:15]
	v_mfma_f32_16x16x32_bf16 v[8:11], v[168:171], v[218:221], v[8:11]
	v_mfma_f32_16x16x32_bf16 v[52:55], v[172:175], v[188:191], v[52:55]
	v_mfma_f32_16x16x32_bf16 v[48:51], v[180:183], v[188:191], v[48:51]
	v_mfma_f32_16x16x32_bf16 v[36:39], v[172:175], v[196:199], v[36:39]
	v_mfma_f32_16x16x32_bf16 v[32:35], v[180:183], v[196:199], v[32:35]
	v_mfma_f32_16x16x32_bf16 v[20:23], v[172:175], v[204:207], v[20:23]
	v_mfma_f32_16x16x32_bf16 v[16:19], v[180:183], v[204:207], v[16:19]
	v_mfma_f32_16x16x32_bf16 v[4:7], v[172:175], v[214:217], v[4:7]
	v_mfma_f32_16x16x32_bf16 v[0:3], v[180:183], v[214:217], v[0:3]
	v_mfma_f32_16x16x32_bf16 v[52:55], v[176:179], v[192:195], v[52:55]
	v_mfma_f32_16x16x32_bf16 v[48:51], v[184:187], v[192:195], v[48:51]
	v_mfma_f32_16x16x32_bf16 v[36:39], v[176:179], v[200:203], v[36:39]
	v_mfma_f32_16x16x32_bf16 v[32:35], v[184:187], v[200:203], v[32:35]
	v_mfma_f32_16x16x32_bf16 v[20:23], v[176:179], v[210:213], v[20:23]
	v_mfma_f32_16x16x32_bf16 v[16:19], v[184:187], v[210:213], v[16:19]
	v_mfma_f32_16x16x32_bf16 v[4:7], v[176:179], v[218:221], v[4:7]
	v_mfma_f32_16x16x32_bf16 v[0:3], v[184:187], v[218:221], v[0:3]
	s_barrier
	s_add_i32 s50, s50, 2
	s_add_u32 s18, s18, 0x100
	s_addc_u32 s19, s19, 0
	s_add_u32 s48, s48, 0x100
	s_addc_u32 s49, s49, 0
	s_cmp_gt_u32 s50, 13
	s_cbranch_scc0 .LBB0_410
	s_and_b64 vcc, exec, s[6:7]
	s_cbranch_vccz .LBB0_413
	s_barrier

; #define PG8_STAGE(bufoff, gbase, voff) do { _Pragma("unroll") for (int _i = 0; _i < 2; ++_i) \
;         __builtin_amdgcn_global_load_lds((const unsigned*)((const char*)(gbase) + (voff)[_i]), (PG8_LAS unsigned*)(lds + (bufoff) + ldsw + _i * 8192), 16, 0, 0); } while (0)
; #define PG8_LDA(dst, b, h) do { _Pragma("unroll") for (int m = 0; m < 4; ++m) _Pragma("unroll") for (int k = 0; k < 2; ++k) dst[m][k] = *(const PG8_LAS bf16x8*)(lds + PG8_SA(b, h) + aoff + m * 2048 + k * 1024); } while (0)
; #define PG8_LDB(dst, b, h) do { _Pragma("unroll") for (int n = 0; n < 2; ++n) _Pragma("unroll") for (int k = 0; k < 2; ++k) dst[n][k] = *(const PG8_LAS bf16x8*)(lds + PG8_SB(b, h) + boff + n * 2048 + k * 1024); } while (0)
; #define PG8_MMA(ai, bj, At, Bt) do { __builtin_amdgcn_s_setprio(1); _Pragma("unroll") for (int m = 0; m < 4; ++m) _Pragma("unroll") for (int n = 0; n < 2; ++n) _Pragma("unroll") for (int k = 0; k < 2; ++k) \
;         acc[ai][bj][m][n] = __builtin_amdgcn_mfma_f32_16x16x32_bf16(Bt[n][k], At[m][k], acc[ai][bj][m][n], 0, 0, 0); __builtin_amdgcn_s_setprio(0); } while (0)
; #define PG8_WAIT_V(n) asm volatile("s_waitcnt vmcnt(" #n ")" ::: "memory")
; #define PG8_WAIT_L(n) asm volatile("s_waitcnt lgkmcnt(" #n ")" ::: "memory")
; #define PG8_BAR __builtin_amdgcn_s_barrier()
; #define PG8_SCHED __builtin_amdgcn_sched_barrier(0)
; template <class Epi, class Sched, bool ALIGN_EPI = false, bool SP2 = false>
; __device__ __forceinline__ void gemm_phase(PG8_LAS unsigned char* lds, const Gemm g, const Sched& S, const Epi& E) {
;     ...
;             PG8_LDB(B0, 0, 0); PG8_LDB(B1, 0, 1); PG8_SCHED; PG8_LDA(At, 0, 0); PG8_STAGE(PG8_SA(1, 1), a1 + hstep, voffA);
;             PG8_WAIT_V(8); PG8_WAIT_L(0); PG8_BAR; PG8_MMA(0, 0, At, B0); PG8_MMA(0, 1, At, B1); PG8_BAR; PG8_SCHED;
;             PG8_LDA(At, 0, 1); PG8_STAGE(PG8_SB(0, 0), b2, voffB); PG8_STAGE(PG8_SB(0, 1), b2 + hstep, voffB); PG8_STAGE(PG8_SA(0, 0), a2, voffA);
;             PG8_WAIT_V(8); PG8_WAIT_L(0); PG8_BAR; PG8_MMA(1, 0, At, B0); PG8_MMA(1, 1, At, B1); PG8_BAR; PG8_SCHED;
.LBB0_1013:
	ds_read_b128 v[144:147], v151
	ds_read_b128 v[156:159], v151 offset:1024
	ds_read_b128 v[160:163], v151 offset:2048
	ds_read_b128 v[164:167], v151 offset:3072
	ds_read_b128 v[168:171], v152
	ds_read_b128 v[172:175], v152 offset:1024
	ds_read_b128 v[176:179], v152 offset:2048
	ds_read_b128 v[180:183], v152 offset:3072
	s_add_u32 s28, s26, 0xfffc0080
	s_addc_u32 s29, s27, -1
	s_cmp_eq_u32 s53, 12
	s_cselect_b32 s31, s17, s29
	s_cselect_b32 s30, s23, s28
	s_cselect_b32 s29, s15, s52
	s_cselect_b32 s28, s50, s51
	v_lshl_add_u64 v[218:219], s[26:27], 0, v[136:137]
	s_add_i32 m0, s25, 0xc000
	ds_read_b128 v[184:187], v153
	ds_read_b128 v[188:191], v153 offset:1024
	ds_read_b128 v[192:195], v153 offset:2048
	ds_read_b128 v[196:199], v153 offset:3072
	ds_read_b128 v[200:203], v153 offset:4096
	ds_read_b128 v[204:207], v153 offset:5120
	ds_read_b128 v[210:213], v153 offset:6144
	ds_read_b128 v[214:217], v153 offset:7168
	global_load_lds_dwordx4 v[218:219], off
	v_lshl_add_u64 v[218:219], s[26:27], 0, v[138:139]
	s_add_i32 m0, s25, 0xe000
	s_nop 0
	global_load_lds_dwordx4 v[218:219], off
	s_waitcnt vmcnt(8)
	s_waitcnt lgkmcnt(0)
	s_barrier
	s_waitcnt lgkmcnt(0)
	v_mfma_f32_16x16x32_bf16 v[124:127], v[144:147], v[184:187], v[124:127]
	v_mfma_f32_16x16x32_bf16 v[120:123], v[160:163], v[184:187], v[120:123]
	v_mfma_f32_16x16x32_bf16 v[108:111], v[144:147], v[192:195], v[108:111]
	v_mfma_f32_16x16x32_bf16 v[104:107], v[160:163], v[192:195], v[104:107]
	v_mfma_f32_16x16x32_bf16 v[92:95], v[144:147], v[200:203], v[92:95]
	v_mfma_f32_16x16x32_bf16 v[88:91], v[160:163], v[200:203], v[88:91]
	v_mfma_f32_16x16x32_bf16 v[76:79], v[144:147], v[210:213], v[76:79]
	v_mfma_f32_16x16x32_bf16 v[72:75], v[160:163], v[210:213], v[72:75]
	v_mfma_f32_16x16x32_bf16 v[124:127], v[156:159], v[188:191], v[124:127]
	v_mfma_f32_16x16x32_bf16 v[120:123], v[164:167], v[188:191], v[120:123]
	v_mfma_f32_16x16x32_bf16 v[108:111], v[156:159], v[196:199], v[108:111]
	v_mfma_f32_16x16x32_bf16 v[104:107], v[164:167], v[196:199], v[104:107]
	v_mfma_f32_16x16x32_bf16 v[92:95], v[156:159], v[204:207], v[92:95]
	v_mfma_f32_16x16x32_bf16 v[88:91], v[164:167], v[204:207], v[88:91]
	v_mfma_f32_16x16x32_bf16 v[76:79], v[156:159], v[214:217], v[76:79]
	v_mfma_f32_16x16x32_bf16 v[72:75], v[164:167], v[214:217], v[72:75]
	v_mfma_f32_16x16x32_bf16 v[116:119], v[168:171], v[184:187], v[116:119]
	v_mfma_f32_16x16x32_bf16 v[112:115], v[176:179], v[184:187], v[112:115]
	v_mfma_f32_16x16x32_bf16 v[100:103], v[168:171], v[192:195], v[100:103]
	v_mfma_f32_16x16x32_bf16 v[96:99], v[176:179], v[192:195], v[96:99]
	v_mfma_f32_16x16x32_bf16 v[84:87], v[168:171], v[200:203], v[84:87]
	v_mfma_f32_16x16x32_bf16 v[80:83], v[176:179], v[200:203], v[80:83]
	v_mfma_f32_16x16x32_bf16 v[68:71], v[168:171], v[210:213], v[68:71]
	v_mfma_f32_16x16x32_bf16 v[64:67], v[176:179], v[210:213], v[64:67]
	v_mfma_f32_16x16x32_bf16 v[116:119], v[172:175], v[188:191], v[116:119]
	v_mfma_f32_16x16x32_bf16 v[112:115], v[180:183], v[188:191], v[112:115]
	v_mfma_f32_16x16x32_bf16 v[100:103], v[172:175], v[196:199], v[100:103]
	v_mfma_f32_16x16x32_bf16 v[96:99], v[180:183], v[196:199], v[96:99]
	v_mfma_f32_16x16x32_bf16 v[84:87], v[172:175], v[204:207], v[84:87]
	v_mfma_f32_16x16x32_bf16 v[80:83], v[180:183], v[204:207], v[80:83]
	v_mfma_f32_16x16x32_bf16 v[68:71], v[172:175], v[214:217], v[68:71]
	v_mfma_f32_16x16x32_bf16 v[64:67], v[180:183], v[214:217], v[64:67]
	s_barrier
	s_add_i32 s54, s48, s38
	v_lshl_add_u64 v[218:219], s[28:29], 0, v[130:131]
	s_mov_b32 m0, s54
	ds_read_b128 v[184:187], v153 offset:16384
	ds_read_b128 v[188:191], v153 offset:17408
	ds_read_b128 v[192:195], v153 offset:18432
	ds_read_b128 v[196:199], v153 offset:19456
	ds_read_b128 v[200:203], v153 offset:20480
	ds_read_b128 v[204:207], v153 offset:21504
	ds_read_b128 v[210:213], v153 offset:22528
	ds_read_b128 v[214:217], v153 offset:23552
	global_load_lds_dwordx4 v[218:219], off
	s_add_i32 m0, s54, 0x2000
	s_add_u32 s54, s28, 0x40000
	v_lshl_add_u64 v[220:221], s[28:29], 0, v[134:135]
	s_addc_u32 s55, s29, 0
	s_add_i32 s56, s49, s38
	global_load_lds_dwordx4 v[220:221], off
	v_lshl_add_u64 v[222:223], s[54:55], 0, v[130:131]
	s_mov_b32 m0, s56
	v_lshl_add_u64 v[224:225], s[30:31], 0, v[132:133]
	global_load_lds_dwordx4 v[222:223], off
	v_lshl_add_u64 v[222:223], s[54:55], 0, v[134:135]
	s_add_i32 m0, s56, 0x2000
	s_nop 0
	global_load_lds_dwordx4 v[222:223], off
	v_lshl_add_u64 v[222:223], s[30:31], 0, v[128:129]
	s_mov_b32 m0, s25
	s_nop 0
	global_load_lds_dwordx4 v[222:223], off
	s_mov_b32 m0, s39
	s_nop 0
	global_load_lds_dwordx4 v[224:225], off
	s_waitcnt vmcnt(8)
	s_waitcnt lgkmcnt(0)
	s_barrier
; #define PG8_STAGE(bufoff, gbase, voff) do { _Pragma("unroll") for (int _i = 0; _i < 2; ++_i) \
;         __builtin_amdgcn_global_load_lds((const unsigned*)((const char*)(gbase) + (voff)[_i]), (PG8_LAS unsigned*)(lds + (bufoff) + ldsw + _i * 8192), 16, 0, 0); } while (0)
; #define PG8_LDA(dst, b, h) do { _Pragma("unroll") for (int m = 0; m < 4; ++m) _Pragma("unroll") for (int k = 0; k < 2; ++k) dst[m][k] = *(const PG8_LAS bf16x8*)(lds + PG8_SA(b, h) + aoff + m * 2048 + k * 1024); } while (0)
; #define PG8_LDB(dst, b, h) do { _Pragma("unroll") for (int n = 0; n < 2; ++n) _Pragma("unroll") for (int k = 0; k < 2; ++k) dst[n][k] = *(const PG8_LAS bf16x8*)(lds + PG8_SB(b, h) + boff + n * 2048 + k * 1024); } while (0)
; #define PG8_MMA(ai, bj, At, Bt) do { __builtin_amdgcn_s_setprio(1); _Pragma("unroll") for (int m = 0; m < 4; ++m) _Pragma("unroll") for (int n = 0; n < 2; ++n) _Pragma("unroll") for (int k = 0; k < 2; ++k) \
;         acc[ai][bj][m][n] = __builtin_amdgcn_mfma_f32_16x16x32_bf16(Bt[n][k], At[m][k], acc[ai][bj][m][n], 0, 0, 0); __builtin_amdgcn_s_setprio(0); } while (0)
; #define PG8_WAIT_V(n) asm volatile("s_waitcnt vmcnt(" #n ")" ::: "memory")
; #define PG8_WAIT_L(n) asm volatile("s_waitcnt lgkmcnt(" #n ")" ::: "memory")
; #define PG8_BAR __builtin_amdgcn_s_barrier()
; #define PG8_SCHED __builtin_amdgcn_sched_barrier(0)
; template <class Epi, class Sched, bool ALIGN_EPI = false, bool SP2 = false>
; __device__ __forceinline__ void gemm_phase(PG8_LAS unsigned char* lds, const Gemm g, const Sched& S, const Epi& E) {
;     ...
;             PG8_WAIT_V(8); PG8_WAIT_L(0); PG8_BAR; PG8_MMA(1, 0, At, B0); PG8_MMA(1, 1, At, B1); PG8_BAR; PG8_SCHED;
;             PG8_LDB(B0, 1, 0); PG8_LDB(B1, 1, 1); PG8_SCHED; PG8_LDA(At, 1, 0); PG8_STAGE(PG8_SA(0, 1), a2 + hstep, voffA);
;             PG8_WAIT_V(8); PG8_WAIT_L(0); PG8_BAR; PG8_MMA(0, 0, At, B0); PG8_MMA(0, 1, At, B1); PG8_BAR; PG8_SCHED;
	s_waitcnt lgkmcnt(0)
	v_mfma_f32_16x16x32_bf16 v[60:63], v[144:147], v[184:187], v[60:63]
	v_mfma_f32_16x16x32_bf16 v[56:59], v[160:163], v[184:187], v[56:59]
	v_mfma_f32_16x16x32_bf16 v[44:47], v[144:147], v[192:195], v[44:47]
	v_mfma_f32_16x16x32_bf16 v[40:43], v[160:163], v[192:195], v[40:43]
	v_mfma_f32_16x16x32_bf16 v[28:31], v[144:147], v[200:203], v[28:31]
	v_mfma_f32_16x16x32_bf16 v[24:27], v[160:163], v[200:203], v[24:27]
	v_mfma_f32_16x16x32_bf16 v[12:15], v[144:147], v[210:213], v[12:15]
	v_mfma_f32_16x16x32_bf16 v[8:11], v[160:163], v[210:213], v[8:11]
	v_mfma_f32_16x16x32_bf16 v[60:63], v[156:159], v[188:191], v[60:63]
	v_mfma_f32_16x16x32_bf16 v[56:59], v[164:167], v[188:191], v[56:59]
	v_mfma_f32_16x16x32_bf16 v[44:47], v[156:159], v[196:199], v[44:47]
	v_mfma_f32_16x16x32_bf16 v[40:43], v[164:167], v[196:199], v[40:43]
	v_mfma_f32_16x16x32_bf16 v[28:31], v[156:159], v[204:207], v[28:31]
	v_mfma_f32_16x16x32_bf16 v[24:27], v[164:167], v[204:207], v[24:27]
	v_mfma_f32_16x16x32_bf16 v[12:15], v[156:159], v[214:217], v[12:15]
	v_mfma_f32_16x16x32_bf16 v[8:11], v[164:167], v[214:217], v[8:11]
	v_mfma_f32_16x16x32_bf16 v[52:55], v[168:171], v[184:187], v[52:55]
	v_mfma_f32_16x16x32_bf16 v[48:51], v[176:179], v[184:187], v[48:51]
	v_mfma_f32_16x16x32_bf16 v[36:39], v[168:171], v[192:195], v[36:39]
	v_mfma_f32_16x16x32_bf16 v[32:35], v[176:179], v[192:195], v[32:35]
	v_mfma_f32_16x16x32_bf16 v[20:23], v[168:171], v[200:203], v[20:23]
	v_mfma_f32_16x16x32_bf16 v[16:19], v[176:179], v[200:203], v[16:19]
	v_mfma_f32_16x16x32_bf16 v[4:7], v[168:171], v[210:213], v[4:7]
	v_mfma_f32_16x16x32_bf16 v[0:3], v[176:179], v[210:213], v[0:3]
	v_mfma_f32_16x16x32_bf16 v[52:55], v[172:175], v[188:191], v[52:55]
	v_mfma_f32_16x16x32_bf16 v[48:51], v[180:183], v[188:191], v[48:51]
	v_mfma_f32_16x16x32_bf16 v[36:39], v[172:175], v[196:199], v[36:39]
	v_mfma_f32_16x16x32_bf16 v[32:35], v[180:183], v[196:199], v[32:35]
	v_mfma_f32_16x16x32_bf16 v[20:23], v[172:175], v[204:207], v[20:23]
	v_mfma_f32_16x16x32_bf16 v[16:19], v[180:183], v[204:207], v[16:19]
	v_mfma_f32_16x16x32_bf16 v[4:7], v[172:175], v[214:217], v[4:7]
	v_mfma_f32_16x16x32_bf16 v[0:3], v[180:183], v[214:217], v[0:3]
	s_barrier
	s_add_i32 s54, 0, 0x18000
	v_add_u32_e32 v155, s54, v149
	s_add_i32 s55, 0, 0x1c000
	ds_read_b128 v[144:147], v155
	ds_read_b128 v[156:159], v155 offset:1024
	ds_read_b128 v[160:163], v155 offset:2048
	ds_read_b128 v[164:167], v155 offset:3072
	v_add_u32_e32 v155, s55, v149
	ds_read_b128 v[168:171], v155
	ds_read_b128 v[172:175], v155 offset:1024
	ds_read_b128 v[176:179], v155 offset:2048
	ds_read_b128 v[180:183], v155 offset:3072
	s_add_u32 s30, s30, 0x40000
	s_addc_u32 s31, s31, 0
	s_mov_b32 m0, s40
	v_lshl_add_u64 v[226:227], s[30:31], 0, v[128:129]
	ds_read_b128 v[184:187], v153 offset:32768
	ds_read_b128 v[188:191], v153 offset:33792
	ds_read_b128 v[192:195], v153 offset:34816
	ds_read_b128 v[196:199], v153 offset:35840
	ds_read_b128 v[200:203], v153 offset:36864
	ds_read_b128 v[204:207], v153 offset:37888
	ds_read_b128 v[210:213], v153 offset:38912
	ds_read_b128 v[214:217], v153 offset:39936
	global_load_lds_dwordx4 v[226:227], off
	v_lshl_add_u64 v[226:227], s[30:31], 0, v[132:133]
	s_mov_b32 m0, s41
	s_nop 0
	global_load_lds_dwordx4 v[226:227], off
	s_waitcnt vmcnt(8)
	s_waitcnt lgkmcnt(0)
	s_barrier
	s_waitcnt lgkmcnt(0)
	v_mfma_f32_16x16x32_bf16 v[124:127], v[144:147], v[184:187], v[124:127]
	v_mfma_f32_16x16x32_bf16 v[120:123], v[160:163], v[184:187], v[120:123]
	v_mfma_f32_16x16x32_bf16 v[108:111], v[144:147], v[192:195], v[108:111]
	v_mfma_f32_16x16x32_bf16 v[104:107], v[160:163], v[192:195], v[104:107]
	v_mfma_f32_16x16x32_bf16 v[92:95], v[144:147], v[200:203], v[92:95]
	v_mfma_f32_16x16x32_bf16 v[88:91], v[160:163], v[200:203], v[88:91]
	v_mfma_f32_16x16x32_bf16 v[76:79], v[144:147], v[210:213], v[76:79]
	v_mfma_f32_16x16x32_bf16 v[72:75], v[160:163], v[210:213], v[72:75]
	v_mfma_f32_16x16x32_bf16 v[124:127], v[156:159], v[188:191], v[124:127]
	v_mfma_f32_16x16x32_bf16 v[120:123], v[164:167], v[188:191], v[120:123]
	v_mfma_f32_16x16x32_bf16 v[108:111], v[156:159], v[196:199], v[108:111]
	v_mfma_f32_16x16x32_bf16 v[104:107], v[164:167], v[196:199], v[104:107]
	v_mfma_f32_16x16x32_bf16 v[92:95], v[156:159], v[204:207], v[92:95]
	v_mfma_f32_16x16x32_bf16 v[88:91], v[164:167], v[204:207], v[88:91]
	v_mfma_f32_16x16x32_bf16 v[76:79], v[156:159], v[214:217], v[76:79]
	v_mfma_f32_16x16x32_bf16 v[72:75], v[164:167], v[214:217], v[72:75]
	v_mfma_f32_16x16x32_bf16 v[116:119], v[168:171], v[184:187], v[116:119]
	v_mfma_f32_16x16x32_bf16 v[112:115], v[176:179], v[184:187], v[112:115]
	v_mfma_f32_16x16x32_bf16 v[100:103], v[168:171], v[192:195], v[100:103]
	v_mfma_f32_16x16x32_bf16 v[96:99], v[176:179], v[192:195], v[96:99]
	v_mfma_f32_16x16x32_bf16 v[84:87], v[168:171], v[200:203], v[84:87]
	v_mfma_f32_16x16x32_bf16 v[80:83], v[176:179], v[200:203], v[80:83]
	v_mfma_f32_16x16x32_bf16 v[68:71], v[168:171], v[210:213], v[68:71]
	v_mfma_f32_16x16x32_bf16 v[64:67], v[176:179], v[210:213], v[64:67]
	v_mfma_f32_16x16x32_bf16 v[116:119], v[172:175], v[188:191], v[116:119]
	v_mfma_f32_16x16x32_bf16 v[112:115], v[180:183], v[188:191], v[112:115]
	v_mfma_f32_16x16x32_bf16 v[100:103], v[172:175], v[196:199], v[100:103]
	v_mfma_f32_16x16x32_bf16 v[96:99], v[180:183], v[196:199], v[96:99]
	v_mfma_f32_16x16x32_bf16 v[84:87], v[172:175], v[204:207], v[84:87]
	v_mfma_f32_16x16x32_bf16 v[80:83], v[180:183], v[204:207], v[80:83]
	v_mfma_f32_16x16x32_bf16 v[68:71], v[172:175], v[214:217], v[68:71]
	v_mfma_f32_16x16x32_bf16 v[64:67], v[180:183], v[214:217], v[64:67]
	s_barrier
; #define PG8_STAGE(bufoff, gbase, voff) do { _Pragma("unroll") for (int _i = 0; _i < 2; ++_i) \
;         __builtin_amdgcn_global_load_lds((const unsigned*)((const char*)(gbase) + (voff)[_i]), (PG8_LAS unsigned*)(lds + (bufoff) + ldsw + _i * 8192), 16, 0, 0); } while (0)
; #define PG8_LDA(dst, b, h) do { _Pragma("unroll") for (int m = 0; m < 4; ++m) _Pragma("unroll") for (int k = 0; k < 2; ++k) dst[m][k] = *(const PG8_LAS bf16x8*)(lds + PG8_SA(b, h) + aoff + m * 2048 + k * 1024); } while (0)
; #define PG8_MMA(ai, bj, At, Bt) do { __builtin_amdgcn_s_setprio(1); _Pragma("unroll") for (int m = 0; m < 4; ++m) _Pragma("unroll") for (int n = 0; n < 2; ++n) _Pragma("unroll") for (int k = 0; k < 2; ++k) \
;         acc[ai][bj][m][n] = __builtin_amdgcn_mfma_f32_16x16x32_bf16(Bt[n][k], At[m][k], acc[ai][bj][m][n], 0, 0, 0); __builtin_amdgcn_s_setprio(0); } while (0)
; #define PG8_WAIT_V(n) asm volatile("s_waitcnt vmcnt(" #n ")" ::: "memory")
; #define PG8_WAIT_L(n) asm volatile("s_waitcnt lgkmcnt(" #n ")" ::: "memory")
; #define PG8_BAR __builtin_amdgcn_s_barrier()
; #define PG8_SCHED __builtin_amdgcn_sched_barrier(0)
; template <class Epi, class Sched, bool ALIGN_EPI = false, bool SP2 = false>
; __device__ __forceinline__ void gemm_phase(PG8_LAS unsigned char* lds, const Gemm g, const Sched& S, const Epi& E) {
;     ...
;         for (int t = 0; t < nt; t += 2) {
;             const bool last = (t == nt - 2);
;             const char* a1 = cA + (size_t)(t + 1) * kstep;
;             const char* a2 = last ? nA : cA + (size_t)(t + 2) * kstep; const char* b2 = last ? nB : cB + (size_t)(t + 2) * kstep;
;             const char* a3 = a2 + kstep; const char* b3 = b2 + kstep;
;             if (last && has_next) S.a_ready(nxt);
;     ...
;             PG8_LDA(At, 1, 1); PG8_STAGE(PG8_SB(1, 0), b3, voffB); PG8_STAGE(PG8_SB(1, 1), b3 + hstep, voffB); PG8_STAGE(PG8_SA(1, 0), a3, voffA);
;             PG8_WAIT_V(8); PG8_WAIT_L(0); PG8_BAR; PG8_MMA(1, 0, At, B0); PG8_MMA(1, 1, At, B1); PG8_BAR; PG8_SCHED;
	s_add_i32 s30, s54, s38
	v_lshl_add_u64 v[218:219], v[218:219], 0, s[10:11]
	s_mov_b32 m0, s30
	ds_read_b128 v[184:187], v153 offset:49152
	ds_read_b128 v[188:191], v153 offset:50176
	ds_read_b128 v[192:195], v153 offset:51200
	ds_read_b128 v[196:199], v153 offset:52224
	ds_read_b128 v[200:203], v153 offset:53248
	ds_read_b128 v[204:207], v153 offset:54272
	ds_read_b128 v[210:213], v153 offset:55296
	ds_read_b128 v[214:217], v153 offset:56320
	global_load_lds_dwordx4 v[218:219], off
	s_add_i32 m0, s30, 0x2000
	s_add_u32 s28, s28, 0x40080
	v_lshl_add_u64 v[218:219], v[220:221], 0, s[10:11]
	s_addc_u32 s29, s29, 0
	s_add_i32 s30, s55, s38
	global_load_lds_dwordx4 v[218:219], off
	v_lshl_add_u64 v[218:219], s[28:29], 0, v[130:131]
	s_mov_b32 m0, s30
	s_nop 0
	global_load_lds_dwordx4 v[218:219], off
	v_lshl_add_u64 v[218:219], s[28:29], 0, v[134:135]
	s_add_i32 m0, s30, 0x2000
	s_nop 0
	global_load_lds_dwordx4 v[218:219], off
	v_lshl_add_u64 v[218:219], v[222:223], 0, s[10:11]
	s_mov_b32 m0, s43
	s_nop 0
	global_load_lds_dwordx4 v[218:219], off
	v_lshl_add_u64 v[218:219], v[224:225], 0, s[10:11]
	s_mov_b32 m0, s44
	s_nop 0
	global_load_lds_dwordx4 v[218:219], off
	s_waitcnt vmcnt(8)
	s_waitcnt lgkmcnt(0)
	s_barrier
	s_waitcnt lgkmcnt(0)
	v_mfma_f32_16x16x32_bf16 v[60:63], v[144:147], v[184:187], v[60:63]
	v_mfma_f32_16x16x32_bf16 v[56:59], v[160:163], v[184:187], v[56:59]
	v_mfma_f32_16x16x32_bf16 v[44:47], v[144:147], v[192:195], v[44:47]
	v_mfma_f32_16x16x32_bf16 v[40:43], v[160:163], v[192:195], v[40:43]
	v_mfma_f32_16x16x32_bf16 v[28:31], v[144:147], v[200:203], v[28:31]
	v_mfma_f32_16x16x32_bf16 v[24:27], v[160:163], v[200:203], v[24:27]
	v_mfma_f32_16x16x32_bf16 v[12:15], v[144:147], v[210:213], v[12:15]
	v_mfma_f32_16x16x32_bf16 v[8:11], v[160:163], v[210:213], v[8:11]
	v_mfma_f32_16x16x32_bf16 v[60:63], v[156:159], v[188:191], v[60:63]
	v_mfma_f32_16x16x32_bf16 v[56:59], v[164:167], v[188:191], v[56:59]
	v_mfma_f32_16x16x32_bf16 v[44:47], v[156:159], v[196:199], v[44:47]
	v_mfma_f32_16x16x32_bf16 v[40:43], v[164:167], v[196:199], v[40:43]
	v_mfma_f32_16x16x32_bf16 v[28:31], v[156:159], v[204:207], v[28:31]
	v_mfma_f32_16x16x32_bf16 v[24:27], v[164:167], v[204:207], v[24:27]
	v_mfma_f32_16x16x32_bf16 v[12:15], v[156:159], v[214:217], v[12:15]
	v_mfma_f32_16x16x32_bf16 v[8:11], v[164:167], v[214:217], v[8:11]
	v_mfma_f32_16x16x32_bf16 v[52:55], v[168:171], v[184:187], v[52:55]
	v_mfma_f32_16x16x32_bf16 v[48:51], v[176:179], v[184:187], v[48:51]
	v_mfma_f32_16x16x32_bf16 v[36:39], v[168:171], v[192:195], v[36:39]
	v_mfma_f32_16x16x32_bf16 v[32:35], v[176:179], v[192:195], v[32:35]
	v_mfma_f32_16x16x32_bf16 v[20:23], v[168:171], v[200:203], v[20:23]
	v_mfma_f32_16x16x32_bf16 v[16:19], v[176:179], v[200:203], v[16:19]
	v_mfma_f32_16x16x32_bf16 v[4:7], v[168:171], v[210:213], v[4:7]
	v_mfma_f32_16x16x32_bf16 v[0:3], v[176:179], v[210:213], v[0:3]
	v_mfma_f32_16x16x32_bf16 v[52:55], v[172:175], v[188:191], v[52:55]
	v_mfma_f32_16x16x32_bf16 v[48:51], v[180:183], v[188:191], v[48:51]
	v_mfma_f32_16x16x32_bf16 v[36:39], v[172:175], v[196:199], v[36:39]
	v_mfma_f32_16x16x32_bf16 v[32:35], v[180:183], v[196:199], v[32:35]
	v_mfma_f32_16x16x32_bf16 v[20:23], v[172:175], v[204:207], v[20:23]
	v_mfma_f32_16x16x32_bf16 v[16:19], v[180:183], v[204:207], v[16:19]
	v_mfma_f32_16x16x32_bf16 v[4:7], v[172:175], v[214:217], v[4:7]
	v_mfma_f32_16x16x32_bf16 v[0:3], v[180:183], v[214:217], v[0:3]
	s_barrier
	s_add_i32 s53, s53, 2
	s_add_u32 s26, s26, 0x100
	s_addc_u32 s27, s27, 0
	s_add_u32 s51, s51, 0x100
	s_addc_u32 s52, s52, 0
	s_cmp_gt_u32 s53, 13
	s_cbranch_scc0 .LBB0_1013
	s_and_b64 vcc, exec, s[12:13]
	s_cbranch_vccz .LBB0_1016
	s_barrier

; #define PG8_STAGE(bufoff, gbase, voff) do { _Pragma("unroll") for (int _i = 0; _i < 2; ++_i) \
;         __builtin_amdgcn_global_load_lds((const unsigned*)((const char*)(gbase) + (voff)[_i]), (PG8_LAS unsigned*)(lds + (bufoff) + ldsw + _i * 8192), 16, 0, 0); } while (0)
; #define PG8_LDA(dst, b, h) do { _Pragma("unroll") for (int m = 0; m < 4; ++m) _Pragma("unroll") for (int k = 0; k < 2; ++k) dst[m][k] = *(const PG8_LAS bf16x8*)(lds + PG8_SA(b, h) + aoff + m * 2048 + k * 1024); } while (0)
; #define PG8_LDB(dst, b, h) do { _Pragma("unroll") for (int n = 0; n < 2; ++n) _Pragma("unroll") for (int k = 0; k < 2; ++k) dst[n][k] = *(const PG8_LAS bf16x8*)(lds + PG8_SB(b, h) + boff + n * 2048 + k * 1024); } while (0)
; #define PG8_MMA(ai, bj, At, Bt) do { __builtin_amdgcn_s_setprio(1); _Pragma("unroll") for (int m = 0; m < 4; ++m) _Pragma("unroll") for (int n = 0; n < 2; ++n) _Pragma("unroll") for (int k = 0; k < 2; ++k) \
;         acc[ai][bj][m][n] = __builtin_amdgcn_mfma_f32_16x16x32_bf16(Bt[n][k], At[m][k], acc[ai][bj][m][n], 0, 0, 0); __builtin_amdgcn_s_setprio(0); } while (0)
; #define PG8_WAIT_V(n) asm volatile("s_waitcnt vmcnt(" #n ")" ::: "memory")
; #define PG8_WAIT_L(n) asm volatile("s_waitcnt lgkmcnt(" #n ")" ::: "memory")
; #define PG8_BAR __builtin_amdgcn_s_barrier()
; #define PG8_SCHED __builtin_amdgcn_sched_barrier(0)
; template <class Epi, class Sched, bool ALIGN_EPI = false, bool SP2 = false>
; __device__ __forceinline__ void gemm_phase(PG8_LAS unsigned char* lds, const Gemm g, const Sched& S, const Epi& E) {
;     ...
;             PG8_LDB(B0, 0, 0); PG8_LDB(B1, 0, 1); PG8_SCHED; PG8_LDA(At, 0, 0); PG8_STAGE(PG8_SA(1, 1), a1 + hstep, voffA);
;             PG8_WAIT_V(8); PG8_WAIT_L(0); PG8_BAR; PG8_MMA(0, 0, At, B0); PG8_MMA(0, 1, At, B1); PG8_BAR; PG8_SCHED;
;             PG8_LDA(At, 0, 1); PG8_STAGE(PG8_SB(0, 0), b2, voffB); PG8_STAGE(PG8_SB(0, 1), b2 + hstep, voffB); PG8_STAGE(PG8_SA(0, 0), a2, voffA);
;             PG8_WAIT_V(8); PG8_WAIT_L(0); PG8_BAR; PG8_MMA(1, 0, At, B0); PG8_MMA(1, 1, At, B1); PG8_BAR; PG8_SCHED;
.LBB0_1103:
	ds_read_b128 v[144:147], v155
	ds_read_b128 v[148:151], v155 offset:1024
	ds_read_b128 v[160:163], v155 offset:2048
	ds_read_b128 v[164:167], v155 offset:3072
	ds_read_b128 v[168:171], v156
	ds_read_b128 v[172:175], v156 offset:1024
	ds_read_b128 v[176:179], v156 offset:2048
	ds_read_b128 v[180:183], v156 offset:3072
	s_add_u32 s24, s22, 0xfffc0080
	s_addc_u32 s25, s23, -1
	s_cmp_eq_u32 s53, 12
	s_cselect_b32 s27, s15, s25
	s_cselect_b32 s26, s49, s24
	s_cselect_b32 s25, s13, s52
	s_cselect_b32 s24, s50, s51
	v_lshl_add_u64 v[218:219], s[22:23], 0, v[136:137]
	s_add_i32 m0, s21, 0xc000
	ds_read_b128 v[184:187], v157
	ds_read_b128 v[188:191], v157 offset:1024
	ds_read_b128 v[192:195], v157 offset:2048
	ds_read_b128 v[196:199], v157 offset:3072
	ds_read_b128 v[200:203], v157 offset:4096
	ds_read_b128 v[204:207], v157 offset:5120
	ds_read_b128 v[210:213], v157 offset:6144
	ds_read_b128 v[214:217], v157 offset:7168
	global_load_lds_dwordx4 v[218:219], off
	v_lshl_add_u64 v[218:219], s[22:23], 0, v[138:139]
	s_add_i32 m0, s21, 0xe000
	s_nop 0
	global_load_lds_dwordx4 v[218:219], off
	s_waitcnt vmcnt(8)
	s_waitcnt lgkmcnt(0)
	s_barrier
	s_waitcnt lgkmcnt(0)
	v_mfma_f32_16x16x32_bf16 v[124:127], v[144:147], v[184:187], v[124:127]
	v_mfma_f32_16x16x32_bf16 v[120:123], v[160:163], v[184:187], v[120:123]
	v_mfma_f32_16x16x32_bf16 v[108:111], v[144:147], v[192:195], v[108:111]
	v_mfma_f32_16x16x32_bf16 v[104:107], v[160:163], v[192:195], v[104:107]
	v_mfma_f32_16x16x32_bf16 v[92:95], v[144:147], v[200:203], v[92:95]
	v_mfma_f32_16x16x32_bf16 v[88:91], v[160:163], v[200:203], v[88:91]
	v_mfma_f32_16x16x32_bf16 v[76:79], v[144:147], v[210:213], v[76:79]
	v_mfma_f32_16x16x32_bf16 v[72:75], v[160:163], v[210:213], v[72:75]
	v_mfma_f32_16x16x32_bf16 v[124:127], v[148:151], v[188:191], v[124:127]
	v_mfma_f32_16x16x32_bf16 v[120:123], v[164:167], v[188:191], v[120:123]
	v_mfma_f32_16x16x32_bf16 v[108:111], v[148:151], v[196:199], v[108:111]
	v_mfma_f32_16x16x32_bf16 v[104:107], v[164:167], v[196:199], v[104:107]
	v_mfma_f32_16x16x32_bf16 v[92:95], v[148:151], v[204:207], v[92:95]
	v_mfma_f32_16x16x32_bf16 v[88:91], v[164:167], v[204:207], v[88:91]
	v_mfma_f32_16x16x32_bf16 v[76:79], v[148:151], v[214:217], v[76:79]
	v_mfma_f32_16x16x32_bf16 v[72:75], v[164:167], v[214:217], v[72:75]
	v_mfma_f32_16x16x32_bf16 v[116:119], v[168:171], v[184:187], v[116:119]
	v_mfma_f32_16x16x32_bf16 v[112:115], v[176:179], v[184:187], v[112:115]
	v_mfma_f32_16x16x32_bf16 v[100:103], v[168:171], v[192:195], v[100:103]
	v_mfma_f32_16x16x32_bf16 v[96:99], v[176:179], v[192:195], v[96:99]
	v_mfma_f32_16x16x32_bf16 v[84:87], v[168:171], v[200:203], v[84:87]
	v_mfma_f32_16x16x32_bf16 v[80:83], v[176:179], v[200:203], v[80:83]
	v_mfma_f32_16x16x32_bf16 v[68:71], v[168:171], v[210:213], v[68:71]
	v_mfma_f32_16x16x32_bf16 v[64:67], v[176:179], v[210:213], v[64:67]
	v_mfma_f32_16x16x32_bf16 v[116:119], v[172:175], v[188:191], v[116:119]
	v_mfma_f32_16x16x32_bf16 v[112:115], v[180:183], v[188:191], v[112:115]
	v_mfma_f32_16x16x32_bf16 v[100:103], v[172:175], v[196:199], v[100:103]
	v_mfma_f32_16x16x32_bf16 v[96:99], v[180:183], v[196:199], v[96:99]
	v_mfma_f32_16x16x32_bf16 v[84:87], v[172:175], v[204:207], v[84:87]
	v_mfma_f32_16x16x32_bf16 v[80:83], v[180:183], v[204:207], v[80:83]
	v_mfma_f32_16x16x32_bf16 v[68:71], v[172:175], v[214:217], v[68:71]
	v_mfma_f32_16x16x32_bf16 v[64:67], v[180:183], v[214:217], v[64:67]
	s_barrier
	s_add_i32 s54, s45, s34
	v_lshl_add_u64 v[218:219], s[24:25], 0, v[130:131]
	s_mov_b32 m0, s54
	ds_read_b128 v[184:187], v157 offset:16384
	ds_read_b128 v[188:191], v157 offset:17408
	ds_read_b128 v[192:195], v157 offset:18432
	ds_read_b128 v[196:199], v157 offset:19456
	ds_read_b128 v[200:203], v157 offset:20480
	ds_read_b128 v[204:207], v157 offset:21504
	ds_read_b128 v[210:213], v157 offset:22528
	ds_read_b128 v[214:217], v157 offset:23552
	global_load_lds_dwordx4 v[218:219], off
	s_add_i32 m0, s54, 0x2000
	s_add_u32 s54, s24, 0x40000
	v_lshl_add_u64 v[220:221], s[24:25], 0, v[134:135]
	s_addc_u32 s55, s25, 0
	s_add_i32 s56, s46, s34
	global_load_lds_dwordx4 v[220:221], off
	v_lshl_add_u64 v[222:223], s[54:55], 0, v[130:131]
	s_mov_b32 m0, s56
	v_lshl_add_u64 v[224:225], s[26:27], 0, v[132:133]
	global_load_lds_dwordx4 v[222:223], off
	v_lshl_add_u64 v[222:223], s[54:55], 0, v[134:135]
	s_add_i32 m0, s56, 0x2000
	s_nop 0
	global_load_lds_dwordx4 v[222:223], off
	v_lshl_add_u64 v[222:223], s[26:27], 0, v[128:129]
	s_mov_b32 m0, s21
	s_nop 0
	global_load_lds_dwordx4 v[222:223], off
	s_mov_b32 m0, s37
	s_nop 0
	global_load_lds_dwordx4 v[224:225], off
	s_waitcnt vmcnt(8)
	s_waitcnt lgkmcnt(0)
	s_barrier
; #define PG8_STAGE(bufoff, gbase, voff) do { _Pragma("unroll") for (int _i = 0; _i < 2; ++_i) \
;         __builtin_amdgcn_global_load_lds((const unsigned*)((const char*)(gbase) + (voff)[_i]), (PG8_LAS unsigned*)(lds + (bufoff) + ldsw + _i * 8192), 16, 0, 0); } while (0)
; #define PG8_LDA(dst, b, h) do { _Pragma("unroll") for (int m = 0; m < 4; ++m) _Pragma("unroll") for (int k = 0; k < 2; ++k) dst[m][k] = *(const PG8_LAS bf16x8*)(lds + PG8_SA(b, h) + aoff + m * 2048 + k * 1024); } while (0)
; #define PG8_LDB(dst, b, h) do { _Pragma("unroll") for (int n = 0; n < 2; ++n) _Pragma("unroll") for (int k = 0; k < 2; ++k) dst[n][k] = *(const PG8_LAS bf16x8*)(lds + PG8_SB(b, h) + boff + n * 2048 + k * 1024); } while (0)
; #define PG8_MMA(ai, bj, At, Bt) do { __builtin_amdgcn_s_setprio(1); _Pragma("unroll") for (int m = 0; m < 4; ++m) _Pragma("unroll") for (int n = 0; n < 2; ++n) _Pragma("unroll") for (int k = 0; k < 2; ++k) \
;         acc[ai][bj][m][n] = __builtin_amdgcn_mfma_f32_16x16x32_bf16(Bt[n][k], At[m][k], acc[ai][bj][m][n], 0, 0, 0); __builtin_amdgcn_s_setprio(0); } while (0)
; #define PG8_WAIT_V(n) asm volatile("s_waitcnt vmcnt(" #n ")" ::: "memory")
; #define PG8_WAIT_L(n) asm volatile("s_waitcnt lgkmcnt(" #n ")" ::: "memory")
; #define PG8_BAR __builtin_amdgcn_s_barrier()
; #define PG8_SCHED __builtin_amdgcn_sched_barrier(0)
; template <class Epi, class Sched, bool ALIGN_EPI = false, bool SP2 = false>
; __device__ __forceinline__ void gemm_phase(PG8_LAS unsigned char* lds, const Gemm g, const Sched& S, const Epi& E) {
;     ...
;             PG8_WAIT_V(8); PG8_WAIT_L(0); PG8_BAR; PG8_MMA(1, 0, At, B0); PG8_MMA(1, 1, At, B1); PG8_BAR; PG8_SCHED;
;             PG8_LDB(B0, 1, 0); PG8_LDB(B1, 1, 1); PG8_SCHED; PG8_LDA(At, 1, 0); PG8_STAGE(PG8_SA(0, 1), a2 + hstep, voffA);
;             PG8_WAIT_V(8); PG8_WAIT_L(0); PG8_BAR; PG8_MMA(0, 0, At, B0); PG8_MMA(0, 1, At, B1); PG8_BAR; PG8_SCHED;
	s_waitcnt lgkmcnt(0)
	v_mfma_f32_16x16x32_bf16 v[60:63], v[144:147], v[184:187], v[60:63]
	v_mfma_f32_16x16x32_bf16 v[56:59], v[160:163], v[184:187], v[56:59]
	v_mfma_f32_16x16x32_bf16 v[44:47], v[144:147], v[192:195], v[44:47]
	v_mfma_f32_16x16x32_bf16 v[40:43], v[160:163], v[192:195], v[40:43]
	v_mfma_f32_16x16x32_bf16 v[28:31], v[144:147], v[200:203], v[28:31]
	v_mfma_f32_16x16x32_bf16 v[24:27], v[160:163], v[200:203], v[24:27]
	v_mfma_f32_16x16x32_bf16 v[12:15], v[144:147], v[210:213], v[12:15]
	v_mfma_f32_16x16x32_bf16 v[8:11], v[160:163], v[210:213], v[8:11]
	v_mfma_f32_16x16x32_bf16 v[60:63], v[148:151], v[188:191], v[60:63]
	v_mfma_f32_16x16x32_bf16 v[56:59], v[164:167], v[188:191], v[56:59]
	v_mfma_f32_16x16x32_bf16 v[44:47], v[148:151], v[196:199], v[44:47]
	v_mfma_f32_16x16x32_bf16 v[40:43], v[164:167], v[196:199], v[40:43]
	v_mfma_f32_16x16x32_bf16 v[28:31], v[148:151], v[204:207], v[28:31]
	v_mfma_f32_16x16x32_bf16 v[24:27], v[164:167], v[204:207], v[24:27]
	v_mfma_f32_16x16x32_bf16 v[12:15], v[148:151], v[214:217], v[12:15]
	v_mfma_f32_16x16x32_bf16 v[8:11], v[164:167], v[214:217], v[8:11]
	v_mfma_f32_16x16x32_bf16 v[52:55], v[168:171], v[184:187], v[52:55]
	v_mfma_f32_16x16x32_bf16 v[48:51], v[176:179], v[184:187], v[48:51]
	v_mfma_f32_16x16x32_bf16 v[36:39], v[168:171], v[192:195], v[36:39]
	v_mfma_f32_16x16x32_bf16 v[32:35], v[176:179], v[192:195], v[32:35]
	v_mfma_f32_16x16x32_bf16 v[20:23], v[168:171], v[200:203], v[20:23]
	v_mfma_f32_16x16x32_bf16 v[16:19], v[176:179], v[200:203], v[16:19]
	v_mfma_f32_16x16x32_bf16 v[4:7], v[168:171], v[210:213], v[4:7]
	v_mfma_f32_16x16x32_bf16 v[0:3], v[176:179], v[210:213], v[0:3]
	v_mfma_f32_16x16x32_bf16 v[52:55], v[172:175], v[188:191], v[52:55]
	v_mfma_f32_16x16x32_bf16 v[48:51], v[180:183], v[188:191], v[48:51]
	v_mfma_f32_16x16x32_bf16 v[36:39], v[172:175], v[196:199], v[36:39]
	v_mfma_f32_16x16x32_bf16 v[32:35], v[180:183], v[196:199], v[32:35]
	v_mfma_f32_16x16x32_bf16 v[20:23], v[172:175], v[204:207], v[20:23]
	v_mfma_f32_16x16x32_bf16 v[16:19], v[180:183], v[204:207], v[16:19]
	v_mfma_f32_16x16x32_bf16 v[4:7], v[172:175], v[214:217], v[4:7]
	v_mfma_f32_16x16x32_bf16 v[0:3], v[180:183], v[214:217], v[0:3]
	s_barrier
	s_add_i32 s54, 0, 0x18000
	v_add_u32_e32 v159, s54, v153
	s_add_i32 s55, 0, 0x1c000
	ds_read_b128 v[144:147], v159
	ds_read_b128 v[148:151], v159 offset:1024
	ds_read_b128 v[160:163], v159 offset:2048
	ds_read_b128 v[164:167], v159 offset:3072
	v_add_u32_e32 v159, s55, v153
	ds_read_b128 v[168:171], v159
	ds_read_b128 v[172:175], v159 offset:1024
	ds_read_b128 v[176:179], v159 offset:2048
	ds_read_b128 v[180:183], v159 offset:3072
	s_add_u32 s26, s26, 0x40000
	s_addc_u32 s27, s27, 0
	s_mov_b32 m0, s38
	v_lshl_add_u64 v[226:227], s[26:27], 0, v[128:129]
	ds_read_b128 v[184:187], v157 offset:32768
	ds_read_b128 v[188:191], v157 offset:33792
	ds_read_b128 v[192:195], v157 offset:34816
	ds_read_b128 v[196:199], v157 offset:35840
	ds_read_b128 v[200:203], v157 offset:36864
	ds_read_b128 v[204:207], v157 offset:37888
	ds_read_b128 v[210:213], v157 offset:38912
	ds_read_b128 v[214:217], v157 offset:39936
	global_load_lds_dwordx4 v[226:227], off
	v_lshl_add_u64 v[226:227], s[26:27], 0, v[132:133]
	s_mov_b32 m0, s39
	s_nop 0
	global_load_lds_dwordx4 v[226:227], off
	s_waitcnt vmcnt(8)
	s_waitcnt lgkmcnt(0)
	s_barrier
	s_waitcnt lgkmcnt(0)
	v_mfma_f32_16x16x32_bf16 v[124:127], v[144:147], v[184:187], v[124:127]
	v_mfma_f32_16x16x32_bf16 v[120:123], v[160:163], v[184:187], v[120:123]
	v_mfma_f32_16x16x32_bf16 v[108:111], v[144:147], v[192:195], v[108:111]
	v_mfma_f32_16x16x32_bf16 v[104:107], v[160:163], v[192:195], v[104:107]
	v_mfma_f32_16x16x32_bf16 v[92:95], v[144:147], v[200:203], v[92:95]
	v_mfma_f32_16x16x32_bf16 v[88:91], v[160:163], v[200:203], v[88:91]
	v_mfma_f32_16x16x32_bf16 v[76:79], v[144:147], v[210:213], v[76:79]
	v_mfma_f32_16x16x32_bf16 v[72:75], v[160:163], v[210:213], v[72:75]
	v_mfma_f32_16x16x32_bf16 v[124:127], v[148:151], v[188:191], v[124:127]
	v_mfma_f32_16x16x32_bf16 v[120:123], v[164:167], v[188:191], v[120:123]
	v_mfma_f32_16x16x32_bf16 v[108:111], v[148:151], v[196:199], v[108:111]
	v_mfma_f32_16x16x32_bf16 v[104:107], v[164:167], v[196:199], v[104:107]
	v_mfma_f32_16x16x32_bf16 v[92:95], v[148:151], v[204:207], v[92:95]
	v_mfma_f32_16x16x32_bf16 v[88:91], v[164:167], v[204:207], v[88:91]
	v_mfma_f32_16x16x32_bf16 v[76:79], v[148:151], v[214:217], v[76:79]
	v_mfma_f32_16x16x32_bf16 v[72:75], v[164:167], v[214:217], v[72:75]
	v_mfma_f32_16x16x32_bf16 v[116:119], v[168:171], v[184:187], v[116:119]
	v_mfma_f32_16x16x32_bf16 v[112:115], v[176:179], v[184:187], v[112:115]
	v_mfma_f32_16x16x32_bf16 v[100:103], v[168:171], v[192:195], v[100:103]
	v_mfma_f32_16x16x32_bf16 v[96:99], v[176:179], v[192:195], v[96:99]
	v_mfma_f32_16x16x32_bf16 v[84:87], v[168:171], v[200:203], v[84:87]
	v_mfma_f32_16x16x32_bf16 v[80:83], v[176:179], v[200:203], v[80:83]
	v_mfma_f32_16x16x32_bf16 v[68:71], v[168:171], v[210:213], v[68:71]
	v_mfma_f32_16x16x32_bf16 v[64:67], v[176:179], v[210:213], v[64:67]
	v_mfma_f32_16x16x32_bf16 v[116:119], v[172:175], v[188:191], v[116:119]
	v_mfma_f32_16x16x32_bf16 v[112:115], v[180:183], v[188:191], v[112:115]
	v_mfma_f32_16x16x32_bf16 v[100:103], v[172:175], v[196:199], v[100:103]
	v_mfma_f32_16x16x32_bf16 v[96:99], v[180:183], v[196:199], v[96:99]
	v_mfma_f32_16x16x32_bf16 v[84:87], v[172:175], v[204:207], v[84:87]
	v_mfma_f32_16x16x32_bf16 v[80:83], v[180:183], v[204:207], v[80:83]
	v_mfma_f32_16x16x32_bf16 v[68:71], v[172:175], v[214:217], v[68:71]
	v_mfma_f32_16x16x32_bf16 v[64:67], v[180:183], v[214:217], v[64:67]
	s_barrier
; #define PG8_STAGE(bufoff, gbase, voff) do { _Pragma("unroll") for (int _i = 0; _i < 2; ++_i) \
;         __builtin_amdgcn_global_load_lds((const unsigned*)((const char*)(gbase) + (voff)[_i]), (PG8_LAS unsigned*)(lds + (bufoff) + ldsw + _i * 8192), 16, 0, 0); } while (0)
; #define PG8_LDA(dst, b, h) do { _Pragma("unroll") for (int m = 0; m < 4; ++m) _Pragma("unroll") for (int k = 0; k < 2; ++k) dst[m][k] = *(const PG8_LAS bf16x8*)(lds + PG8_SA(b, h) + aoff + m * 2048 + k * 1024); } while (0)
; #define PG8_MMA(ai, bj, At, Bt) do { __builtin_amdgcn_s_setprio(1); _Pragma("unroll") for (int m = 0; m < 4; ++m) _Pragma("unroll") for (int n = 0; n < 2; ++n) _Pragma("unroll") for (int k = 0; k < 2; ++k) \
;         acc[ai][bj][m][n] = __builtin_amdgcn_mfma_f32_16x16x32_bf16(Bt[n][k], At[m][k], acc[ai][bj][m][n], 0, 0, 0); __builtin_amdgcn_s_setprio(0); } while (0)
; #define PG8_WAIT_V(n) asm volatile("s_waitcnt vmcnt(" #n ")" ::: "memory")
; #define PG8_WAIT_L(n) asm volatile("s_waitcnt lgkmcnt(" #n ")" ::: "memory")
; #define PG8_BAR __builtin_amdgcn_s_barrier()
; #define PG8_SCHED __builtin_amdgcn_sched_barrier(0)
; template <class Epi, class Sched, bool ALIGN_EPI = false, bool SP2 = false>
; __device__ __forceinline__ void gemm_phase(PG8_LAS unsigned char* lds, const Gemm g, const Sched& S, const Epi& E) {
;     ...
;         for (int t = 0; t < nt; t += 2) {
;             const bool last = (t == nt - 2);
;             const char* a1 = cA + (size_t)(t + 1) * kstep;
;             const char* a2 = last ? nA : cA + (size_t)(t + 2) * kstep; const char* b2 = last ? nB : cB + (size_t)(t + 2) * kstep;
;             const char* a3 = a2 + kstep; const char* b3 = b2 + kstep;
;             if (last && has_next) S.a_ready(nxt);
;     ...
;             PG8_LDA(At, 1, 1); PG8_STAGE(PG8_SB(1, 0), b3, voffB); PG8_STAGE(PG8_SB(1, 1), b3 + hstep, voffB); PG8_STAGE(PG8_SA(1, 0), a3, voffA);
;             PG8_WAIT_V(8); PG8_WAIT_L(0); PG8_BAR; PG8_MMA(1, 0, At, B0); PG8_MMA(1, 1, At, B1); PG8_BAR; PG8_SCHED;
	s_add_i32 s26, s54, s34
	v_lshl_add_u64 v[218:219], v[218:219], 0, s[8:9]
	s_mov_b32 m0, s26
	ds_read_b128 v[184:187], v157 offset:49152
	ds_read_b128 v[188:191], v157 offset:50176
	ds_read_b128 v[192:195], v157 offset:51200
	ds_read_b128 v[196:199], v157 offset:52224
	ds_read_b128 v[200:203], v157 offset:53248
	ds_read_b128 v[204:207], v157 offset:54272
	ds_read_b128 v[210:213], v157 offset:55296
	ds_read_b128 v[214:217], v157 offset:56320
	global_load_lds_dwordx4 v[218:219], off
	s_add_i32 m0, s26, 0x2000
	s_add_u32 s24, s24, 0x40080
	v_lshl_add_u64 v[218:219], v[220:221], 0, s[8:9]
	s_addc_u32 s25, s25, 0
	s_add_i32 s26, s55, s34
	global_load_lds_dwordx4 v[218:219], off
	v_lshl_add_u64 v[218:219], s[24:25], 0, v[130:131]
	s_mov_b32 m0, s26
	s_nop 0
	global_load_lds_dwordx4 v[218:219], off
	v_lshl_add_u64 v[218:219], s[24:25], 0, v[134:135]
	s_add_i32 m0, s26, 0x2000
	s_nop 0
	global_load_lds_dwordx4 v[218:219], off
	v_lshl_add_u64 v[218:219], v[222:223], 0, s[8:9]
	s_mov_b32 m0, s42
	s_nop 0
	global_load_lds_dwordx4 v[218:219], off
	v_lshl_add_u64 v[218:219], v[224:225], 0, s[8:9]
	s_mov_b32 m0, s43
	s_nop 0
	global_load_lds_dwordx4 v[218:219], off
	s_waitcnt vmcnt(8)
	s_waitcnt lgkmcnt(0)
	s_barrier
	s_waitcnt lgkmcnt(0)
	v_mfma_f32_16x16x32_bf16 v[60:63], v[144:147], v[184:187], v[60:63]
	v_mfma_f32_16x16x32_bf16 v[56:59], v[160:163], v[184:187], v[56:59]
	v_mfma_f32_16x16x32_bf16 v[44:47], v[144:147], v[192:195], v[44:47]
	v_mfma_f32_16x16x32_bf16 v[40:43], v[160:163], v[192:195], v[40:43]
	v_mfma_f32_16x16x32_bf16 v[28:31], v[144:147], v[200:203], v[28:31]
	v_mfma_f32_16x16x32_bf16 v[24:27], v[160:163], v[200:203], v[24:27]
	v_mfma_f32_16x16x32_bf16 v[12:15], v[144:147], v[210:213], v[12:15]
	v_mfma_f32_16x16x32_bf16 v[8:11], v[160:163], v[210:213], v[8:11]
	v_mfma_f32_16x16x32_bf16 v[60:63], v[148:151], v[188:191], v[60:63]
	v_mfma_f32_16x16x32_bf16 v[56:59], v[164:167], v[188:191], v[56:59]
	v_mfma_f32_16x16x32_bf16 v[44:47], v[148:151], v[196:199], v[44:47]
	v_mfma_f32_16x16x32_bf16 v[40:43], v[164:167], v[196:199], v[40:43]
	v_mfma_f32_16x16x32_bf16 v[28:31], v[148:151], v[204:207], v[28:31]
	v_mfma_f32_16x16x32_bf16 v[24:27], v[164:167], v[204:207], v[24:27]
	v_mfma_f32_16x16x32_bf16 v[12:15], v[148:151], v[214:217], v[12:15]
	v_mfma_f32_16x16x32_bf16 v[8:11], v[164:167], v[214:217], v[8:11]
	v_mfma_f32_16x16x32_bf16 v[52:55], v[168:171], v[184:187], v[52:55]
	v_mfma_f32_16x16x32_bf16 v[48:51], v[176:179], v[184:187], v[48:51]
	v_mfma_f32_16x16x32_bf16 v[36:39], v[168:171], v[192:195], v[36:39]
	v_mfma_f32_16x16x32_bf16 v[32:35], v[176:179], v[192:195], v[32:35]
	v_mfma_f32_16x16x32_bf16 v[20:23], v[168:171], v[200:203], v[20:23]
	v_mfma_f32_16x16x32_bf16 v[16:19], v[176:179], v[200:203], v[16:19]
	v_mfma_f32_16x16x32_bf16 v[4:7], v[168:171], v[210:213], v[4:7]
	v_mfma_f32_16x16x32_bf16 v[0:3], v[176:179], v[210:213], v[0:3]
	v_mfma_f32_16x16x32_bf16 v[52:55], v[172:175], v[188:191], v[52:55]
	v_mfma_f32_16x16x32_bf16 v[48:51], v[180:183], v[188:191], v[48:51]
	v_mfma_f32_16x16x32_bf16 v[36:39], v[172:175], v[196:199], v[36:39]
	v_mfma_f32_16x16x32_bf16 v[32:35], v[180:183], v[196:199], v[32:35]
	v_mfma_f32_16x16x32_bf16 v[20:23], v[172:175], v[204:207], v[20:23]
	v_mfma_f32_16x16x32_bf16 v[16:19], v[180:183], v[204:207], v[16:19]
	v_mfma_f32_16x16x32_bf16 v[4:7], v[172:175], v[214:217], v[4:7]
	v_mfma_f32_16x16x32_bf16 v[0:3], v[180:183], v[214:217], v[0:3]
	s_barrier
	s_add_i32 s53, s53, 2
	s_add_u32 s22, s22, 0x100
	s_addc_u32 s23, s23, 0
	s_add_u32 s51, s51, 0x100
	s_addc_u32 s52, s52, 0
	s_cmp_gt_u32 s53, 13
	s_cbranch_scc0 .LBB0_1103
	s_and_b64 vcc, exec, s[10:11]
	s_cbranch_vccz .LBB0_1106
	s_barrier

; #define PG8_STAGE(bufoff, gbase, voff) do { _Pragma("unroll") for (int _i = 0; _i < 2; ++_i) \
;         __builtin_amdgcn_global_load_lds((const unsigned*)((const char*)(gbase) + (voff)[_i]), (PG8_LAS unsigned*)(lds + (bufoff) + ldsw + _i * 8192), 16, 0, 0); } while (0)
; #define PG8_LDA(dst, b, h) do { _Pragma("unroll") for (int m = 0; m < 4; ++m) _Pragma("unroll") for (int k = 0; k < 2; ++k) dst[m][k] = *(const PG8_LAS bf16x8*)(lds + PG8_SA(b, h) + aoff + m * 2048 + k * 1024); } while (0)
; #define PG8_LDB(dst, b, h) do { _Pragma("unroll") for (int n = 0; n < 2; ++n) _Pragma("unroll") for (int k = 0; k < 2; ++k) dst[n][k] = *(const PG8_LAS bf16x8*)(lds + PG8_SB(b, h) + boff + n * 2048 + k * 1024); } while (0)
; #define PG8_MMA(ai, bj, At, Bt) do { __builtin_amdgcn_s_setprio(1); _Pragma("unroll") for (int m = 0; m < 4; ++m) _Pragma("unroll") for (int n = 0; n < 2; ++n) _Pragma("unroll") for (int k = 0; k < 2; ++k) \
;         acc[ai][bj][m][n] = __builtin_amdgcn_mfma_f32_16x16x32_bf16(Bt[n][k], At[m][k], acc[ai][bj][m][n], 0, 0, 0); __builtin_amdgcn_s_setprio(0); } while (0)
; #define PG8_WAIT_V(n) asm volatile("s_waitcnt vmcnt(" #n ")" ::: "memory")
; #define PG8_WAIT_L(n) asm volatile("s_waitcnt lgkmcnt(" #n ")" ::: "memory")
; #define PG8_BAR __builtin_amdgcn_s_barrier()
; #define PG8_SCHED __builtin_amdgcn_sched_barrier(0)
; template <class Epi, class Sched, bool ALIGN_EPI = false, bool SP2 = false>
; __device__ __forceinline__ void gemm_phase(PG8_LAS unsigned char* lds, const Gemm g, const Sched& S, const Epi& E) {
;     ...
;             PG8_LDB(B0, 0, 0); PG8_LDB(B1, 0, 1); PG8_SCHED; PG8_LDA(At, 0, 0); PG8_STAGE(PG8_SA(1, 1), a1 + hstep, voffA);
;             PG8_WAIT_V(8); PG8_WAIT_L(0); PG8_BAR; PG8_MMA(0, 0, At, B0); PG8_MMA(0, 1, At, B1); PG8_BAR; PG8_SCHED;
;             PG8_LDA(At, 0, 1); PG8_STAGE(PG8_SB(0, 0), b2, voffB); PG8_STAGE(PG8_SB(0, 1), b2 + hstep, voffB); PG8_STAGE(PG8_SA(0, 0), a2, voffA);
;             PG8_WAIT_V(8); PG8_WAIT_L(0); PG8_BAR; PG8_MMA(1, 0, At, B0); PG8_MMA(1, 1, At, B1); PG8_BAR; PG8_SCHED;
.LBB0_1190:
	ds_read_b128 v[144:147], v151
	ds_read_b128 v[154:157], v151 offset:1024
	ds_read_b128 v[158:161], v151 offset:2048
	ds_read_b128 v[162:165], v151 offset:3072
	ds_read_b128 v[166:169], v152
	ds_read_b128 v[170:173], v152 offset:1024
	ds_read_b128 v[174:177], v152 offset:2048
	ds_read_b128 v[178:181], v152 offset:3072
	s_add_u32 s18, s16, 0xfff50080
	s_addc_u32 s19, s17, -1
	s_cmp_eq_u32 s46, 40
	s_cselect_b32 s21, s3, s19
	s_cselect_b32 s20, s2, s18
	s_cselect_b32 s19, s15, s45
	s_cselect_b32 s18, s14, s44
	v_lshl_add_u64 v[214:215], s[16:17], 0, v[136:137]
	s_add_i32 m0, s28, 0xc000
	ds_read_b128 v[182:185], v153
	ds_read_b128 v[186:189], v153 offset:1024
	ds_read_b128 v[190:193], v153 offset:2048
	ds_read_b128 v[194:197], v153 offset:3072
	ds_read_b128 v[198:201], v153 offset:4096
	ds_read_b128 v[202:205], v153 offset:5120
	ds_read_b128 v[206:209], v153 offset:6144
	ds_read_b128 v[210:213], v153 offset:7168
	global_load_lds_dwordx4 v[214:215], off
	v_lshl_add_u64 v[214:215], s[16:17], 0, v[138:139]
	s_add_i32 m0, s28, 0xe000
	s_nop 0
	global_load_lds_dwordx4 v[214:215], off
	s_waitcnt vmcnt(8)
	s_waitcnt lgkmcnt(0)
	s_barrier
	s_waitcnt lgkmcnt(0)
	v_mfma_f32_16x16x32_bf16 v[124:127], v[144:147], v[182:185], v[124:127]
	v_mfma_f32_16x16x32_bf16 v[120:123], v[158:161], v[182:185], v[120:123]
	v_mfma_f32_16x16x32_bf16 v[108:111], v[144:147], v[190:193], v[108:111]
	v_mfma_f32_16x16x32_bf16 v[104:107], v[158:161], v[190:193], v[104:107]
	v_mfma_f32_16x16x32_bf16 v[92:95], v[144:147], v[198:201], v[92:95]
	v_mfma_f32_16x16x32_bf16 v[88:91], v[158:161], v[198:201], v[88:91]
	v_mfma_f32_16x16x32_bf16 v[76:79], v[144:147], v[206:209], v[76:79]
	v_mfma_f32_16x16x32_bf16 v[72:75], v[158:161], v[206:209], v[72:75]
	v_mfma_f32_16x16x32_bf16 v[124:127], v[154:157], v[186:189], v[124:127]
	v_mfma_f32_16x16x32_bf16 v[120:123], v[162:165], v[186:189], v[120:123]
	v_mfma_f32_16x16x32_bf16 v[108:111], v[154:157], v[194:197], v[108:111]
	v_mfma_f32_16x16x32_bf16 v[104:107], v[162:165], v[194:197], v[104:107]
	v_mfma_f32_16x16x32_bf16 v[92:95], v[154:157], v[202:205], v[92:95]
	v_mfma_f32_16x16x32_bf16 v[88:91], v[162:165], v[202:205], v[88:91]
	v_mfma_f32_16x16x32_bf16 v[76:79], v[154:157], v[210:213], v[76:79]
	v_mfma_f32_16x16x32_bf16 v[72:75], v[162:165], v[210:213], v[72:75]
	v_mfma_f32_16x16x32_bf16 v[116:119], v[166:169], v[182:185], v[116:119]
	v_mfma_f32_16x16x32_bf16 v[112:115], v[174:177], v[182:185], v[112:115]
	v_mfma_f32_16x16x32_bf16 v[100:103], v[166:169], v[190:193], v[100:103]
	v_mfma_f32_16x16x32_bf16 v[96:99], v[174:177], v[190:193], v[96:99]
	v_mfma_f32_16x16x32_bf16 v[84:87], v[166:169], v[198:201], v[84:87]
	v_mfma_f32_16x16x32_bf16 v[80:83], v[174:177], v[198:201], v[80:83]
	v_mfma_f32_16x16x32_bf16 v[68:71], v[166:169], v[206:209], v[68:71]
	v_mfma_f32_16x16x32_bf16 v[64:67], v[174:177], v[206:209], v[64:67]
	v_mfma_f32_16x16x32_bf16 v[116:119], v[170:173], v[186:189], v[116:119]
	v_mfma_f32_16x16x32_bf16 v[112:115], v[178:181], v[186:189], v[112:115]
	v_mfma_f32_16x16x32_bf16 v[100:103], v[170:173], v[194:197], v[100:103]
	v_mfma_f32_16x16x32_bf16 v[96:99], v[178:181], v[194:197], v[96:99]
	v_mfma_f32_16x16x32_bf16 v[84:87], v[170:173], v[202:205], v[84:87]
	v_mfma_f32_16x16x32_bf16 v[80:83], v[178:181], v[202:205], v[80:83]
	v_mfma_f32_16x16x32_bf16 v[68:71], v[170:173], v[210:213], v[68:71]
	v_mfma_f32_16x16x32_bf16 v[64:67], v[178:181], v[210:213], v[64:67]
	s_barrier
	s_add_i32 s47, s38, s27
	v_lshl_add_u64 v[214:215], s[18:19], 0, v[130:131]
	s_mov_b32 m0, s47
	ds_read_b128 v[182:185], v153 offset:16384
	ds_read_b128 v[186:189], v153 offset:17408
	ds_read_b128 v[190:193], v153 offset:18432
	ds_read_b128 v[194:197], v153 offset:19456
	ds_read_b128 v[198:201], v153 offset:20480
	ds_read_b128 v[202:205], v153 offset:21504
	ds_read_b128 v[206:209], v153 offset:22528
	ds_read_b128 v[210:213], v153 offset:23552
	global_load_lds_dwordx4 v[214:215], off
	s_add_i32 m0, s47, 0x2000
	s_add_u32 s48, s18, 0xb0000
	v_lshl_add_u64 v[216:217], s[18:19], 0, v[134:135]
	s_addc_u32 s49, s19, 0
	s_add_i32 s47, s39, s27
	global_load_lds_dwordx4 v[216:217], off
	v_lshl_add_u64 v[218:219], s[48:49], 0, v[130:131]
	s_mov_b32 m0, s47
	v_lshl_add_u64 v[220:221], s[20:21], 0, v[132:133]
	global_load_lds_dwordx4 v[218:219], off
	v_lshl_add_u64 v[218:219], s[48:49], 0, v[134:135]
	s_add_i32 m0, s47, 0x2000
	s_nop 0
	global_load_lds_dwordx4 v[218:219], off
	v_lshl_add_u64 v[218:219], s[20:21], 0, v[128:129]
	s_mov_b32 m0, s28
	s_nop 0
	global_load_lds_dwordx4 v[218:219], off
	s_mov_b32 m0, s29
	s_nop 0
	global_load_lds_dwordx4 v[220:221], off
	s_waitcnt vmcnt(8)
	s_waitcnt lgkmcnt(0)
	s_barrier
; #define PG8_STAGE(bufoff, gbase, voff) do { _Pragma("unroll") for (int _i = 0; _i < 2; ++_i) \
;         __builtin_amdgcn_global_load_lds((const unsigned*)((const char*)(gbase) + (voff)[_i]), (PG8_LAS unsigned*)(lds + (bufoff) + ldsw + _i * 8192), 16, 0, 0); } while (0)
; #define PG8_LDA(dst, b, h) do { _Pragma("unroll") for (int m = 0; m < 4; ++m) _Pragma("unroll") for (int k = 0; k < 2; ++k) dst[m][k] = *(const PG8_LAS bf16x8*)(lds + PG8_SA(b, h) + aoff + m * 2048 + k * 1024); } while (0)
; #define PG8_LDB(dst, b, h) do { _Pragma("unroll") for (int n = 0; n < 2; ++n) _Pragma("unroll") for (int k = 0; k < 2; ++k) dst[n][k] = *(const PG8_LAS bf16x8*)(lds + PG8_SB(b, h) + boff + n * 2048 + k * 1024); } while (0)
; #define PG8_MMA(ai, bj, At, Bt) do { __builtin_amdgcn_s_setprio(1); _Pragma("unroll") for (int m = 0; m < 4; ++m) _Pragma("unroll") for (int n = 0; n < 2; ++n) _Pragma("unroll") for (int k = 0; k < 2; ++k) \
;         acc[ai][bj][m][n] = __builtin_amdgcn_mfma_f32_16x16x32_bf16(Bt[n][k], At[m][k], acc[ai][bj][m][n], 0, 0, 0); __builtin_amdgcn_s_setprio(0); } while (0)
; #define PG8_WAIT_V(n) asm volatile("s_waitcnt vmcnt(" #n ")" ::: "memory")
; #define PG8_WAIT_L(n) asm volatile("s_waitcnt lgkmcnt(" #n ")" ::: "memory")
; #define PG8_BAR __builtin_amdgcn_s_barrier()
; #define PG8_SCHED __builtin_amdgcn_sched_barrier(0)
; template <class Epi, class Sched, bool ALIGN_EPI = false, bool SP2 = false>
; __device__ __forceinline__ void gemm_phase(PG8_LAS unsigned char* lds, const Gemm g, const Sched& S, const Epi& E) {
;     ...
;             PG8_WAIT_V(8); PG8_WAIT_L(0); PG8_BAR; PG8_MMA(1, 0, At, B0); PG8_MMA(1, 1, At, B1); PG8_BAR; PG8_SCHED;
;             PG8_LDB(B0, 1, 0); PG8_LDB(B1, 1, 1); PG8_SCHED; PG8_LDA(At, 1, 0); PG8_STAGE(PG8_SA(0, 1), a2 + hstep, voffA);
;             PG8_WAIT_V(8); PG8_WAIT_L(0); PG8_BAR; PG8_MMA(0, 0, At, B0); PG8_MMA(0, 1, At, B1); PG8_BAR; PG8_SCHED;
	s_waitcnt lgkmcnt(0)
	v_mfma_f32_16x16x32_bf16 v[60:63], v[144:147], v[182:185], v[60:63]
	v_mfma_f32_16x16x32_bf16 v[56:59], v[158:161], v[182:185], v[56:59]
	v_mfma_f32_16x16x32_bf16 v[44:47], v[144:147], v[190:193], v[44:47]
	v_mfma_f32_16x16x32_bf16 v[40:43], v[158:161], v[190:193], v[40:43]
	v_mfma_f32_16x16x32_bf16 v[28:31], v[144:147], v[198:201], v[28:31]
	v_mfma_f32_16x16x32_bf16 v[24:27], v[158:161], v[198:201], v[24:27]
	v_mfma_f32_16x16x32_bf16 v[12:15], v[144:147], v[206:209], v[12:15]
	v_mfma_f32_16x16x32_bf16 v[8:11], v[158:161], v[206:209], v[8:11]
	v_mfma_f32_16x16x32_bf16 v[60:63], v[154:157], v[186:189], v[60:63]
	v_mfma_f32_16x16x32_bf16 v[56:59], v[162:165], v[186:189], v[56:59]
	v_mfma_f32_16x16x32_bf16 v[44:47], v[154:157], v[194:197], v[44:47]
	v_mfma_f32_16x16x32_bf16 v[40:43], v[162:165], v[194:197], v[40:43]
	v_mfma_f32_16x16x32_bf16 v[28:31], v[154:157], v[202:205], v[28:31]
	v_mfma_f32_16x16x32_bf16 v[24:27], v[162:165], v[202:205], v[24:27]
	v_mfma_f32_16x16x32_bf16 v[12:15], v[154:157], v[210:213], v[12:15]
	v_mfma_f32_16x16x32_bf16 v[8:11], v[162:165], v[210:213], v[8:11]
	v_mfma_f32_16x16x32_bf16 v[52:55], v[166:169], v[182:185], v[52:55]
	v_mfma_f32_16x16x32_bf16 v[48:51], v[174:177], v[182:185], v[48:51]
	v_mfma_f32_16x16x32_bf16 v[36:39], v[166:169], v[190:193], v[36:39]
	v_mfma_f32_16x16x32_bf16 v[32:35], v[174:177], v[190:193], v[32:35]
	v_mfma_f32_16x16x32_bf16 v[20:23], v[166:169], v[198:201], v[20:23]
	v_mfma_f32_16x16x32_bf16 v[16:19], v[174:177], v[198:201], v[16:19]
	v_mfma_f32_16x16x32_bf16 v[4:7], v[166:169], v[206:209], v[4:7]
	v_mfma_f32_16x16x32_bf16 v[0:3], v[174:177], v[206:209], v[0:3]
	v_mfma_f32_16x16x32_bf16 v[52:55], v[170:173], v[186:189], v[52:55]
	v_mfma_f32_16x16x32_bf16 v[48:51], v[178:181], v[186:189], v[48:51]
	v_mfma_f32_16x16x32_bf16 v[36:39], v[170:173], v[194:197], v[36:39]
	v_mfma_f32_16x16x32_bf16 v[32:35], v[178:181], v[194:197], v[32:35]
	v_mfma_f32_16x16x32_bf16 v[20:23], v[170:173], v[202:205], v[20:23]
	v_mfma_f32_16x16x32_bf16 v[16:19], v[178:181], v[202:205], v[16:19]
	v_mfma_f32_16x16x32_bf16 v[4:7], v[170:173], v[210:213], v[4:7]
	v_mfma_f32_16x16x32_bf16 v[0:3], v[178:181], v[210:213], v[0:3]
	s_barrier
	s_add_i32 s47, 0, 0x18000
	s_add_i32 s48, 0, 0x1c000
	v_add_u32_e32 v162, s47, v149
	v_add_u32_e32 v178, s48, v149
	ds_read_b128 v[144:147], v162
	ds_read_b128 v[154:157], v162 offset:1024
	ds_read_b128 v[158:161], v162 offset:2048
	ds_read_b128 v[162:165], v162 offset:3072
	ds_read_b128 v[166:169], v178
	ds_read_b128 v[170:173], v178 offset:1024
	ds_read_b128 v[174:177], v178 offset:2048
	ds_read_b128 v[178:181], v178 offset:3072
	s_add_u32 s20, s20, 0xb0000
	s_addc_u32 s21, s21, 0
	s_mov_b32 m0, s30
	v_lshl_add_u64 v[222:223], s[20:21], 0, v[128:129]
	ds_read_b128 v[182:185], v153 offset:32768
	ds_read_b128 v[186:189], v153 offset:33792
	ds_read_b128 v[190:193], v153 offset:34816
	ds_read_b128 v[194:197], v153 offset:35840
	ds_read_b128 v[198:201], v153 offset:36864
	ds_read_b128 v[202:205], v153 offset:37888
	ds_read_b128 v[206:209], v153 offset:38912
	ds_read_b128 v[210:213], v153 offset:39936
	global_load_lds_dwordx4 v[222:223], off
	v_lshl_add_u64 v[222:223], s[20:21], 0, v[132:133]
	s_mov_b32 m0, s31
	s_nop 0
	global_load_lds_dwordx4 v[222:223], off
	s_waitcnt vmcnt(8)
	s_waitcnt lgkmcnt(0)
	s_barrier
	s_waitcnt lgkmcnt(0)
	v_mfma_f32_16x16x32_bf16 v[124:127], v[144:147], v[182:185], v[124:127]
	v_mfma_f32_16x16x32_bf16 v[120:123], v[158:161], v[182:185], v[120:123]
	v_mfma_f32_16x16x32_bf16 v[108:111], v[144:147], v[190:193], v[108:111]
	v_mfma_f32_16x16x32_bf16 v[104:107], v[158:161], v[190:193], v[104:107]
	v_mfma_f32_16x16x32_bf16 v[92:95], v[144:147], v[198:201], v[92:95]
	v_mfma_f32_16x16x32_bf16 v[88:91], v[158:161], v[198:201], v[88:91]
	v_mfma_f32_16x16x32_bf16 v[76:79], v[144:147], v[206:209], v[76:79]
	v_mfma_f32_16x16x32_bf16 v[72:75], v[158:161], v[206:209], v[72:75]
	v_mfma_f32_16x16x32_bf16 v[124:127], v[154:157], v[186:189], v[124:127]
	v_mfma_f32_16x16x32_bf16 v[120:123], v[162:165], v[186:189], v[120:123]
	v_mfma_f32_16x16x32_bf16 v[108:111], v[154:157], v[194:197], v[108:111]
	v_mfma_f32_16x16x32_bf16 v[104:107], v[162:165], v[194:197], v[104:107]
	v_mfma_f32_16x16x32_bf16 v[92:95], v[154:157], v[202:205], v[92:95]
	v_mfma_f32_16x16x32_bf16 v[88:91], v[162:165], v[202:205], v[88:91]
	v_mfma_f32_16x16x32_bf16 v[76:79], v[154:157], v[210:213], v[76:79]
	v_mfma_f32_16x16x32_bf16 v[72:75], v[162:165], v[210:213], v[72:75]
	v_mfma_f32_16x16x32_bf16 v[116:119], v[166:169], v[182:185], v[116:119]
	v_mfma_f32_16x16x32_bf16 v[112:115], v[174:177], v[182:185], v[112:115]
	v_mfma_f32_16x16x32_bf16 v[100:103], v[166:169], v[190:193], v[100:103]
	v_mfma_f32_16x16x32_bf16 v[96:99], v[174:177], v[190:193], v[96:99]
	v_mfma_f32_16x16x32_bf16 v[84:87], v[166:169], v[198:201], v[84:87]
	v_mfma_f32_16x16x32_bf16 v[80:83], v[174:177], v[198:201], v[80:83]
	v_mfma_f32_16x16x32_bf16 v[68:71], v[166:169], v[206:209], v[68:71]
	v_mfma_f32_16x16x32_bf16 v[64:67], v[174:177], v[206:209], v[64:67]
	v_mfma_f32_16x16x32_bf16 v[116:119], v[170:173], v[186:189], v[116:119]
	v_mfma_f32_16x16x32_bf16 v[112:115], v[178:181], v[186:189], v[112:115]
	v_mfma_f32_16x16x32_bf16 v[100:103], v[170:173], v[194:197], v[100:103]
	v_mfma_f32_16x16x32_bf16 v[96:99], v[178:181], v[194:197], v[96:99]
	v_mfma_f32_16x16x32_bf16 v[84:87], v[170:173], v[202:205], v[84:87]
	v_mfma_f32_16x16x32_bf16 v[80:83], v[178:181], v[202:205], v[80:83]
	v_mfma_f32_16x16x32_bf16 v[68:71], v[170:173], v[210:213], v[68:71]
	v_mfma_f32_16x16x32_bf16 v[64:67], v[178:181], v[210:213], v[64:67]
	s_barrier
; #define PG8_STAGE(bufoff, gbase, voff) do { _Pragma("unroll") for (int _i = 0; _i < 2; ++_i) \
;         __builtin_amdgcn_global_load_lds((const unsigned*)((const char*)(gbase) + (voff)[_i]), (PG8_LAS unsigned*)(lds + (bufoff) + ldsw + _i * 8192), 16, 0, 0); } while (0)
; #define PG8_LDA(dst, b, h) do { _Pragma("unroll") for (int m = 0; m < 4; ++m) _Pragma("unroll") for (int k = 0; k < 2; ++k) dst[m][k] = *(const PG8_LAS bf16x8*)(lds + PG8_SA(b, h) + aoff + m * 2048 + k * 1024); } while (0)
; #define PG8_MMA(ai, bj, At, Bt) do { __builtin_amdgcn_s_setprio(1); _Pragma("unroll") for (int m = 0; m < 4; ++m) _Pragma("unroll") for (int n = 0; n < 2; ++n) _Pragma("unroll") for (int k = 0; k < 2; ++k) \
;         acc[ai][bj][m][n] = __builtin_amdgcn_mfma_f32_16x16x32_bf16(Bt[n][k], At[m][k], acc[ai][bj][m][n], 0, 0, 0); __builtin_amdgcn_s_setprio(0); } while (0)
; #define PG8_WAIT_V(n) asm volatile("s_waitcnt vmcnt(" #n ")" ::: "memory")
; #define PG8_WAIT_L(n) asm volatile("s_waitcnt lgkmcnt(" #n ")" ::: "memory")
; #define PG8_BAR __builtin_amdgcn_s_barrier()
; #define PG8_SCHED __builtin_amdgcn_sched_barrier(0)
; template <class Epi, class Sched, bool ALIGN_EPI = false, bool SP2 = false>
; __device__ __forceinline__ void gemm_phase(PG8_LAS unsigned char* lds, const Gemm g, const Sched& S, const Epi& E) {
;     ...
;             PG8_LDA(At, 1, 1); PG8_STAGE(PG8_SB(1, 0), b3, voffB); PG8_STAGE(PG8_SB(1, 1), b3 + hstep, voffB); PG8_STAGE(PG8_SA(1, 0), a3, voffA);
;             PG8_WAIT_V(8); PG8_WAIT_L(0); PG8_BAR; PG8_MMA(1, 0, At, B0); PG8_MMA(1, 1, At, B1); PG8_BAR; PG8_SCHED;
	s_add_i32 s20, s47, s27
	v_lshl_add_u64 v[214:215], v[214:215], 0, s[8:9]
	s_mov_b32 m0, s20
	ds_read_b128 v[182:185], v153 offset:49152
	ds_read_b128 v[186:189], v153 offset:50176
	ds_read_b128 v[190:193], v153 offset:51200
	ds_read_b128 v[194:197], v153 offset:52224
	ds_read_b128 v[198:201], v153 offset:53248
	ds_read_b128 v[202:205], v153 offset:54272
	ds_read_b128 v[206:209], v153 offset:55296
	ds_read_b128 v[210:213], v153 offset:56320
	global_load_lds_dwordx4 v[214:215], off
	s_add_i32 m0, s20, 0x2000
	s_add_u32 s18, s18, 0xb0080
	v_lshl_add_u64 v[214:215], v[216:217], 0, s[8:9]
	s_addc_u32 s19, s19, 0
	s_add_i32 s20, s48, s27
	global_load_lds_dwordx4 v[214:215], off
	v_lshl_add_u64 v[214:215], s[18:19], 0, v[130:131]
	s_mov_b32 m0, s20
	s_nop 0
	global_load_lds_dwordx4 v[214:215], off
	v_lshl_add_u64 v[214:215], s[18:19], 0, v[134:135]
	s_add_i32 m0, s20, 0x2000
	s_nop 0
	global_load_lds_dwordx4 v[214:215], off
	v_lshl_add_u64 v[214:215], v[218:219], 0, s[8:9]
	s_mov_b32 m0, s35
	s_nop 0
	global_load_lds_dwordx4 v[214:215], off
	v_lshl_add_u64 v[214:215], v[220:221], 0, s[8:9]
	s_mov_b32 m0, s36
	s_nop 0
	global_load_lds_dwordx4 v[214:215], off
	s_waitcnt vmcnt(8)
	s_waitcnt lgkmcnt(0)
	s_barrier
	s_waitcnt lgkmcnt(0)
	v_mfma_f32_16x16x32_bf16 v[60:63], v[144:147], v[182:185], v[60:63]
	v_mfma_f32_16x16x32_bf16 v[56:59], v[158:161], v[182:185], v[56:59]
	v_mfma_f32_16x16x32_bf16 v[44:47], v[144:147], v[190:193], v[44:47]
	v_mfma_f32_16x16x32_bf16 v[40:43], v[158:161], v[190:193], v[40:43]
	v_mfma_f32_16x16x32_bf16 v[28:31], v[144:147], v[198:201], v[28:31]
	v_mfma_f32_16x16x32_bf16 v[24:27], v[158:161], v[198:201], v[24:27]
	v_mfma_f32_16x16x32_bf16 v[12:15], v[144:147], v[206:209], v[12:15]
	v_mfma_f32_16x16x32_bf16 v[8:11], v[158:161], v[206:209], v[8:11]
	v_mfma_f32_16x16x32_bf16 v[60:63], v[154:157], v[186:189], v[60:63]
	v_mfma_f32_16x16x32_bf16 v[56:59], v[162:165], v[186:189], v[56:59]
	v_mfma_f32_16x16x32_bf16 v[44:47], v[154:157], v[194:197], v[44:47]
	v_mfma_f32_16x16x32_bf16 v[40:43], v[162:165], v[194:197], v[40:43]
	v_mfma_f32_16x16x32_bf16 v[28:31], v[154:157], v[202:205], v[28:31]
	v_mfma_f32_16x16x32_bf16 v[24:27], v[162:165], v[202:205], v[24:27]
	v_mfma_f32_16x16x32_bf16 v[12:15], v[154:157], v[210:213], v[12:15]
	v_mfma_f32_16x16x32_bf16 v[8:11], v[162:165], v[210:213], v[8:11]
	v_mfma_f32_16x16x32_bf16 v[52:55], v[166:169], v[182:185], v[52:55]
	v_mfma_f32_16x16x32_bf16 v[48:51], v[174:177], v[182:185], v[48:51]
	v_mfma_f32_16x16x32_bf16 v[36:39], v[166:169], v[190:193], v[36:39]
	v_mfma_f32_16x16x32_bf16 v[32:35], v[174:177], v[190:193], v[32:35]
	v_mfma_f32_16x16x32_bf16 v[20:23], v[166:169], v[198:201], v[20:23]
	v_mfma_f32_16x16x32_bf16 v[16:19], v[174:177], v[198:201], v[16:19]
	v_mfma_f32_16x16x32_bf16 v[4:7], v[166:169], v[206:209], v[4:7]
	v_mfma_f32_16x16x32_bf16 v[0:3], v[174:177], v[206:209], v[0:3]
	v_mfma_f32_16x16x32_bf16 v[52:55], v[170:173], v[186:189], v[52:55]
	v_mfma_f32_16x16x32_bf16 v[48:51], v[178:181], v[186:189], v[48:51]
	v_mfma_f32_16x16x32_bf16 v[36:39], v[170:173], v[194:197], v[36:39]
	v_mfma_f32_16x16x32_bf16 v[32:35], v[178:181], v[194:197], v[32:35]
	v_mfma_f32_16x16x32_bf16 v[20:23], v[170:173], v[202:205], v[20:23]
	v_mfma_f32_16x16x32_bf16 v[16:19], v[178:181], v[202:205], v[16:19]
	v_mfma_f32_16x16x32_bf16 v[4:7], v[170:173], v[210:213], v[4:7]
	v_mfma_f32_16x16x32_bf16 v[0:3], v[178:181], v[210:213], v[0:3]
	s_barrier
	s_add_i32 s46, s46, 2
	s_add_u32 s16, s16, 0x100
	s_addc_u32 s17, s17, 0
	s_add_u32 s44, s44, 0x100
	s_addc_u32 s45, s45, 0
	s_cmp_gt_u32 s46, 41
	s_cbranch_scc0 .LBB0_1190
	s_and_b64 vcc, exec, s[10:11]
	s_cbranch_vccz .LBB0_1193
	s_barrier
